# v78 + DMA-first only in the 16-read load segments (seg1/seg3); 8-read segments keep ds_reads first
# speedup vs baseline: 1.0166x; 1.0166x over previous
.Lbal_first_21:
	s_add_u32 s26, s24, 0xfffc0080
	s_addc_u32 s27, s25, -1
	s_cmp_eq_u32 s55, 12
	s_cselect_b32 s29, s19, s27
	s_cselect_b32 s28, s51, s26
	s_cselect_b32 s27, s17, s54
	s_cselect_b32 s26, s52, s53
	s_add_i32 m0, s38, 0xc000
	s_nop 0
	global_load_lds_dwordx4 v138, s[24:25]
	s_add_i32 m0, s38, 0xe000
	s_nop 0
	global_load_lds_dwordx4 v136, s[24:25]
	ds_read_b128 v[144:147], v151
	ds_read_b128 v[156:159], v151 offset:1024
	ds_read_b128 v[160:163], v151 offset:2048
	ds_read_b128 v[164:167], v151 offset:3072
	ds_read_b128 v[168:171], v152
	ds_read_b128 v[172:175], v152 offset:1024
	ds_read_b128 v[176:179], v152 offset:2048
	ds_read_b128 v[180:183], v152 offset:3072
	ds_read_b128 v[184:187], v153
	ds_read_b128 v[188:191], v153 offset:1024
	ds_read_b128 v[192:195], v153 offset:2048
	ds_read_b128 v[196:199], v153 offset:3072
	ds_read_b128 v[200:203], v153 offset:4096
	ds_read_b128 v[208:211], v153 offset:5120
	ds_read_b128 v[212:215], v153 offset:6144
	ds_read_b128 v[216:219], v153 offset:7168
	s_waitcnt vmcnt(8)
	s_waitcnt lgkmcnt(0)
	s_barrier
	s_waitcnt lgkmcnt(0)
	v_mfma_f32_16x16x32_bf16 v[124:127], v[144:147], v[184:187], v[124:127]
	v_mfma_f32_16x16x32_bf16 v[120:123], v[160:163], v[184:187], v[120:123]
	v_mfma_f32_16x16x32_bf16 v[108:111], v[144:147], v[192:195], v[108:111]
	v_mfma_f32_16x16x32_bf16 v[104:107], v[160:163], v[192:195], v[104:107]
	v_mfma_f32_16x16x32_bf16 v[92:95], v[144:147], v[200:203], v[92:95]
	v_mfma_f32_16x16x32_bf16 v[88:91], v[160:163], v[200:203], v[88:91]
	v_mfma_f32_16x16x32_bf16 v[76:79], v[144:147], v[212:215], v[76:79]
	v_mfma_f32_16x16x32_bf16 v[72:75], v[160:163], v[212:215], v[72:75]
	v_mfma_f32_16x16x32_bf16 v[124:127], v[156:159], v[188:191], v[124:127]
	v_mfma_f32_16x16x32_bf16 v[120:123], v[164:167], v[188:191], v[120:123]
	v_mfma_f32_16x16x32_bf16 v[108:111], v[156:159], v[196:199], v[108:111]
	v_mfma_f32_16x16x32_bf16 v[104:107], v[164:167], v[196:199], v[104:107]
	v_mfma_f32_16x16x32_bf16 v[92:95], v[156:159], v[208:211], v[92:95]
	v_mfma_f32_16x16x32_bf16 v[88:91], v[164:167], v[208:211], v[88:91]
	v_mfma_f32_16x16x32_bf16 v[76:79], v[156:159], v[216:219], v[76:79]
	v_mfma_f32_16x16x32_bf16 v[72:75], v[164:167], v[216:219], v[72:75]
	v_mfma_f32_16x16x32_bf16 v[116:119], v[168:171], v[184:187], v[116:119]
	v_mfma_f32_16x16x32_bf16 v[112:115], v[176:179], v[184:187], v[112:115]
	v_mfma_f32_16x16x32_bf16 v[100:103], v[168:171], v[192:195], v[100:103]
	v_mfma_f32_16x16x32_bf16 v[96:99], v[176:179], v[192:195], v[96:99]
	v_mfma_f32_16x16x32_bf16 v[84:87], v[168:171], v[200:203], v[84:87]
	v_mfma_f32_16x16x32_bf16 v[80:83], v[176:179], v[200:203], v[80:83]
	v_mfma_f32_16x16x32_bf16 v[68:71], v[168:171], v[212:215], v[68:71]
	v_mfma_f32_16x16x32_bf16 v[64:67], v[176:179], v[212:215], v[64:67]
	v_mfma_f32_16x16x32_bf16 v[116:119], v[172:175], v[188:191], v[116:119]
	v_mfma_f32_16x16x32_bf16 v[112:115], v[180:183], v[188:191], v[112:115]
	v_mfma_f32_16x16x32_bf16 v[100:103], v[172:175], v[196:199], v[100:103]
	v_mfma_f32_16x16x32_bf16 v[96:99], v[180:183], v[196:199], v[96:99]
	v_mfma_f32_16x16x32_bf16 v[84:87], v[172:175], v[208:211], v[84:87]
	v_mfma_f32_16x16x32_bf16 v[80:83], v[180:183], v[208:211], v[80:83]
	v_mfma_f32_16x16x32_bf16 v[68:71], v[172:175], v[216:219], v[68:71]
	v_mfma_f32_16x16x32_bf16 v[64:67], v[180:183], v[216:219], v[64:67]
	s_barrier
	s_add_i32 s56, s48, s35
	s_mov_b32 m0, s56
	ds_read_b128 v[184:187], v153 offset:16384
	ds_read_b128 v[188:191], v153 offset:17408
	ds_read_b128 v[192:195], v153 offset:18432
	ds_read_b128 v[196:199], v153 offset:19456
	ds_read_b128 v[200:203], v153 offset:20480
	ds_read_b128 v[208:211], v153 offset:21504
	ds_read_b128 v[212:215], v153 offset:22528
	ds_read_b128 v[216:219], v153 offset:23552
	global_load_lds_dwordx4 v132, s[26:27]
	s_add_i32 m0, s56, 0x2000
	s_add_u32 s56, s26, 0x40000
	s_mov_b64 s[98:99], s[26:27]
	s_addc_u32 s57, s27, 0
	s_add_i32 s58, s49, s35
	global_load_lds_dwordx4 v128, s[26:27]
	s_mov_b32 m0, s58
	s_mov_b64 s[100:101], s[28:29]
	global_load_lds_dwordx4 v132, s[56:57]
	s_add_i32 m0, s58, 0x2000
	s_nop 0
	global_load_lds_dwordx4 v128, s[56:57]
	s_waitcnt vmcnt(6)
	s_waitcnt lgkmcnt(0)
	s_barrier
	s_waitcnt lgkmcnt(0)
	v_mfma_f32_16x16x32_bf16 v[60:63], v[144:147], v[184:187], v[60:63]
	v_mfma_f32_16x16x32_bf16 v[56:59], v[160:163], v[184:187], v[56:59]
	v_mfma_f32_16x16x32_bf16 v[44:47], v[144:147], v[192:195], v[44:47]
	v_mfma_f32_16x16x32_bf16 v[40:43], v[160:163], v[192:195], v[40:43]
	v_mfma_f32_16x16x32_bf16 v[28:31], v[144:147], v[200:203], v[28:31]
	v_mfma_f32_16x16x32_bf16 v[24:27], v[160:163], v[200:203], v[24:27]
	v_mfma_f32_16x16x32_bf16 v[12:15], v[144:147], v[212:215], v[12:15]
	v_mfma_f32_16x16x32_bf16 v[8:11], v[160:163], v[212:215], v[8:11]
	v_mfma_f32_16x16x32_bf16 v[60:63], v[156:159], v[188:191], v[60:63]
	v_mfma_f32_16x16x32_bf16 v[56:59], v[164:167], v[188:191], v[56:59]
	v_mfma_f32_16x16x32_bf16 v[44:47], v[156:159], v[196:199], v[44:47]
	v_mfma_f32_16x16x32_bf16 v[40:43], v[164:167], v[196:199], v[40:43]
	v_mfma_f32_16x16x32_bf16 v[28:31], v[156:159], v[208:211], v[28:31]
	v_mfma_f32_16x16x32_bf16 v[24:27], v[164:167], v[208:211], v[24:27]
	v_mfma_f32_16x16x32_bf16 v[12:15], v[156:159], v[216:219], v[12:15]
	v_mfma_f32_16x16x32_bf16 v[8:11], v[164:167], v[216:219], v[8:11]
	v_mfma_f32_16x16x32_bf16 v[52:55], v[168:171], v[184:187], v[52:55]
	v_mfma_f32_16x16x32_bf16 v[48:51], v[176:179], v[184:187], v[48:51]
	v_mfma_f32_16x16x32_bf16 v[36:39], v[168:171], v[192:195], v[36:39]
	v_mfma_f32_16x16x32_bf16 v[32:35], v[176:179], v[192:195], v[32:35]
	v_mfma_f32_16x16x32_bf16 v[20:23], v[168:171], v[200:203], v[20:23]
	v_mfma_f32_16x16x32_bf16 v[16:19], v[176:179], v[200:203], v[16:19]
	v_mfma_f32_16x16x32_bf16 v[4:7], v[168:171], v[212:215], v[4:7]
	v_mfma_f32_16x16x32_bf16 v[0:3], v[176:179], v[212:215], v[0:3]
	v_mfma_f32_16x16x32_bf16 v[52:55], v[172:175], v[188:191], v[52:55]
	v_mfma_f32_16x16x32_bf16 v[48:51], v[180:183], v[188:191], v[48:51]
	v_mfma_f32_16x16x32_bf16 v[36:39], v[172:175], v[196:199], v[36:39]
	v_mfma_f32_16x16x32_bf16 v[32:35], v[180:183], v[196:199], v[32:35]
	v_mfma_f32_16x16x32_bf16 v[20:23], v[172:175], v[208:211], v[20:23]
	v_mfma_f32_16x16x32_bf16 v[16:19], v[180:183], v[208:211], v[16:19]
	v_mfma_f32_16x16x32_bf16 v[4:7], v[172:175], v[216:219], v[4:7]
	v_mfma_f32_16x16x32_bf16 v[0:3], v[180:183], v[216:219], v[0:3]
	s_barrier
	s_mov_b32 m0, s38
	s_nop 0
	global_load_lds_dwordx4 v134, s[28:29]
	s_mov_b32 m0, s39
	s_nop 0
	global_load_lds_dwordx4 v130, s[28:29]
	s_add_i32 s56, 0, 0x18000
	s_add_i32 s57, 0, 0x1c000
	s_add_u32 s28, s28, 0x40000
	s_addc_u32 s29, s29, 0
	s_mov_b32 m0, s40
	s_nop 0
	global_load_lds_dwordx4 v134, s[28:29]
	s_mov_b32 m0, s41
	s_nop 0
	global_load_lds_dwordx4 v130, s[28:29]
	v_add_u32_e32 v164, s56, v149
	v_add_u32_e32 v180, s57, v149
	ds_read_b128 v[144:147], v164
	ds_read_b128 v[156:159], v164 offset:1024
	ds_read_b128 v[160:163], v164 offset:2048
	ds_read_b128 v[164:167], v164 offset:3072
	ds_read_b128 v[168:171], v180
	ds_read_b128 v[172:175], v180 offset:1024
	ds_read_b128 v[176:179], v180 offset:2048
	ds_read_b128 v[180:183], v180 offset:3072
	ds_read_b128 v[184:187], v153 offset:32768
	ds_read_b128 v[188:191], v153 offset:33792
	ds_read_b128 v[192:195], v153 offset:34816
	ds_read_b128 v[196:199], v153 offset:35840
	ds_read_b128 v[200:203], v153 offset:36864
	ds_read_b128 v[208:211], v153 offset:37888
	ds_read_b128 v[212:215], v153 offset:38912
	ds_read_b128 v[216:219], v153 offset:39936
	s_waitcnt vmcnt(8)
	s_waitcnt lgkmcnt(0)
	s_barrier
	s_waitcnt lgkmcnt(0)
	v_mfma_f32_16x16x32_bf16 v[124:127], v[144:147], v[184:187], v[124:127]
	v_mfma_f32_16x16x32_bf16 v[120:123], v[160:163], v[184:187], v[120:123]
	v_mfma_f32_16x16x32_bf16 v[108:111], v[144:147], v[192:195], v[108:111]
	v_mfma_f32_16x16x32_bf16 v[104:107], v[160:163], v[192:195], v[104:107]
	v_mfma_f32_16x16x32_bf16 v[92:95], v[144:147], v[200:203], v[92:95]
	v_mfma_f32_16x16x32_bf16 v[88:91], v[160:163], v[200:203], v[88:91]
	v_mfma_f32_16x16x32_bf16 v[76:79], v[144:147], v[212:215], v[76:79]
	v_mfma_f32_16x16x32_bf16 v[72:75], v[160:163], v[212:215], v[72:75]
	v_mfma_f32_16x16x32_bf16 v[124:127], v[156:159], v[188:191], v[124:127]
	v_mfma_f32_16x16x32_bf16 v[120:123], v[164:167], v[188:191], v[120:123]
	v_mfma_f32_16x16x32_bf16 v[108:111], v[156:159], v[196:199], v[108:111]
	v_mfma_f32_16x16x32_bf16 v[104:107], v[164:167], v[196:199], v[104:107]
	v_mfma_f32_16x16x32_bf16 v[92:95], v[156:159], v[208:211], v[92:95]
	v_mfma_f32_16x16x32_bf16 v[88:91], v[164:167], v[208:211], v[88:91]
	v_mfma_f32_16x16x32_bf16 v[76:79], v[156:159], v[216:219], v[76:79]
	v_mfma_f32_16x16x32_bf16 v[72:75], v[164:167], v[216:219], v[72:75]
	v_mfma_f32_16x16x32_bf16 v[116:119], v[168:171], v[184:187], v[116:119]
	v_mfma_f32_16x16x32_bf16 v[112:115], v[176:179], v[184:187], v[112:115]
	v_mfma_f32_16x16x32_bf16 v[100:103], v[168:171], v[192:195], v[100:103]
	v_mfma_f32_16x16x32_bf16 v[96:99], v[176:179], v[192:195], v[96:99]
	v_mfma_f32_16x16x32_bf16 v[84:87], v[168:171], v[200:203], v[84:87]
	v_mfma_f32_16x16x32_bf16 v[80:83], v[176:179], v[200:203], v[80:83]
	v_mfma_f32_16x16x32_bf16 v[68:71], v[168:171], v[212:215], v[68:71]
	v_mfma_f32_16x16x32_bf16 v[64:67], v[176:179], v[212:215], v[64:67]
	v_mfma_f32_16x16x32_bf16 v[116:119], v[172:175], v[188:191], v[116:119]
	v_mfma_f32_16x16x32_bf16 v[112:115], v[180:183], v[188:191], v[112:115]
	v_mfma_f32_16x16x32_bf16 v[100:103], v[172:175], v[196:199], v[100:103]
	v_mfma_f32_16x16x32_bf16 v[96:99], v[180:183], v[196:199], v[96:99]
	v_mfma_f32_16x16x32_bf16 v[84:87], v[172:175], v[208:211], v[84:87]
	v_mfma_f32_16x16x32_bf16 v[80:83], v[180:183], v[208:211], v[80:83]
	v_mfma_f32_16x16x32_bf16 v[68:71], v[172:175], v[216:219], v[68:71]
	v_mfma_f32_16x16x32_bf16 v[64:67], v[180:183], v[216:219], v[64:67]
	s_barrier
	s_add_i32 s28, s56, s35
	s_mov_b32 m0, s28
	ds_read_b128 v[184:187], v153 offset:49152
	ds_read_b128 v[188:191], v153 offset:50176
	ds_read_b128 v[192:195], v153 offset:51200
	ds_read_b128 v[196:199], v153 offset:52224
	ds_read_b128 v[200:203], v153 offset:53248
	ds_read_b128 v[208:211], v153 offset:54272
	ds_read_b128 v[212:215], v153 offset:55296
	ds_read_b128 v[216:219], v153 offset:56320
	global_load_lds_dwordx4 v220, s[26:27]
	s_add_i32 m0, s28, 0x2000
	s_add_u32 s26, s26, 0x40080
	s_addc_u32 s27, s27, 0
	s_add_i32 s28, s57, s35
	global_load_lds_dwordx4 v204, s[98:99]
	s_mov_b32 m0, s28
	s_nop 0
	global_load_lds_dwordx4 v132, s[26:27]
	s_add_i32 m0, s28, 0x2000
	s_nop 0
	global_load_lds_dwordx4 v128, s[26:27]
	s_cmp_lg_u32 s55, 12
	s_cbranch_scc1 .Lbal_last_21
	s_mov_b32 m0, s45
	s_nop 0
	global_load_lds_dwordx4 v221, s[100:101]
	s_mov_b32 m0, s46
	s_nop 0
	global_load_lds_dwordx4 v205, s[100:101]

.Lbal_first_20:
	s_add_u32 s30, s28, 0x100
	s_addc_u32 s31, s29, 0
	s_cmp_eq_u32 s58, 12
	s_cselect_b32 s37, s21, s31
	s_cselect_b32 s36, s27, s30
	s_cselect_b32 s35, s19, s57
	s_cselect_b32 s34, s55, s56
	s_add_i32 m0, s44, 0xc000
	s_nop 0
	global_load_lds_dwordx4 v134, s[28:29]
	s_add_i32 m0, s44, 0xe000
	s_nop 0
	global_load_lds_dwordx4 v132, s[28:29]
	ds_read_b128 v[140:143], v147
	ds_read_b128 v[150:153], v147 offset:1024
	ds_read_b128 v[154:157], v147 offset:2048
	ds_read_b128 v[158:161], v147 offset:3072
	ds_read_b128 v[162:165], v148
	ds_read_b128 v[166:169], v148 offset:1024
	ds_read_b128 v[170:173], v148 offset:2048
	ds_read_b128 v[174:177], v148 offset:3072
	ds_read_b128 v[178:181], v149
	ds_read_b128 v[182:185], v149 offset:1024
	ds_read_b128 v[186:189], v149 offset:2048
	ds_read_b128 v[190:193], v149 offset:3072
	ds_read_b128 v[194:197], v149 offset:4096
	ds_read_b128 v[198:201], v149 offset:5120
	ds_read_b128 v[202:205], v149 offset:6144
	ds_read_b128 v[208:211], v149 offset:7168
	s_waitcnt vmcnt(8)
	s_waitcnt lgkmcnt(0)
	s_barrier
	s_waitcnt lgkmcnt(0)
	v_mfma_f32_16x16x32_bf16 v[124:127], v[140:143], v[178:181], v[124:127]
	v_mfma_f32_16x16x32_bf16 v[120:123], v[154:157], v[178:181], v[120:123]
	v_mfma_f32_16x16x32_bf16 v[108:111], v[140:143], v[186:189], v[108:111]
	v_mfma_f32_16x16x32_bf16 v[104:107], v[154:157], v[186:189], v[104:107]
	v_mfma_f32_16x16x32_bf16 v[92:95], v[140:143], v[194:197], v[92:95]
	v_mfma_f32_16x16x32_bf16 v[88:91], v[154:157], v[194:197], v[88:91]
	v_mfma_f32_16x16x32_bf16 v[76:79], v[140:143], v[202:205], v[76:79]
	v_mfma_f32_16x16x32_bf16 v[72:75], v[154:157], v[202:205], v[72:75]
	v_mfma_f32_16x16x32_bf16 v[124:127], v[150:153], v[182:185], v[124:127]
	v_mfma_f32_16x16x32_bf16 v[120:123], v[158:161], v[182:185], v[120:123]
	v_mfma_f32_16x16x32_bf16 v[108:111], v[150:153], v[190:193], v[108:111]
	v_mfma_f32_16x16x32_bf16 v[104:107], v[158:161], v[190:193], v[104:107]
	v_mfma_f32_16x16x32_bf16 v[92:95], v[150:153], v[198:201], v[92:95]
	v_mfma_f32_16x16x32_bf16 v[88:91], v[158:161], v[198:201], v[88:91]
	v_mfma_f32_16x16x32_bf16 v[76:79], v[150:153], v[208:211], v[76:79]
	v_mfma_f32_16x16x32_bf16 v[72:75], v[158:161], v[208:211], v[72:75]
	v_mfma_f32_16x16x32_bf16 v[116:119], v[162:165], v[178:181], v[116:119]
	v_mfma_f32_16x16x32_bf16 v[112:115], v[170:173], v[178:181], v[112:115]
	v_mfma_f32_16x16x32_bf16 v[100:103], v[162:165], v[186:189], v[100:103]
	v_mfma_f32_16x16x32_bf16 v[96:99], v[170:173], v[186:189], v[96:99]
	v_mfma_f32_16x16x32_bf16 v[84:87], v[162:165], v[194:197], v[84:87]
	v_mfma_f32_16x16x32_bf16 v[80:83], v[170:173], v[194:197], v[80:83]
	v_mfma_f32_16x16x32_bf16 v[68:71], v[162:165], v[202:205], v[68:71]
	v_mfma_f32_16x16x32_bf16 v[64:67], v[170:173], v[202:205], v[64:67]
	v_mfma_f32_16x16x32_bf16 v[116:119], v[166:169], v[182:185], v[116:119]
	v_mfma_f32_16x16x32_bf16 v[112:115], v[174:177], v[182:185], v[112:115]
	v_mfma_f32_16x16x32_bf16 v[100:103], v[166:169], v[190:193], v[100:103]
	v_mfma_f32_16x16x32_bf16 v[96:99], v[174:177], v[190:193], v[96:99]
	v_mfma_f32_16x16x32_bf16 v[84:87], v[166:169], v[198:201], v[84:87]
	v_mfma_f32_16x16x32_bf16 v[80:83], v[174:177], v[198:201], v[80:83]
	v_mfma_f32_16x16x32_bf16 v[68:71], v[166:169], v[208:211], v[68:71]
	v_mfma_f32_16x16x32_bf16 v[64:67], v[174:177], v[208:211], v[64:67]
	s_barrier
	s_add_i32 s28, s52, s43
	s_mov_b32 m0, s28
	ds_read_b128 v[178:181], v149 offset:16384
	ds_read_b128 v[182:185], v149 offset:17408
	ds_read_b128 v[186:189], v149 offset:18432
	ds_read_b128 v[190:193], v149 offset:19456
	ds_read_b128 v[194:197], v149 offset:20480
	ds_read_b128 v[198:201], v149 offset:21504
	ds_read_b128 v[202:205], v149 offset:22528
	ds_read_b128 v[208:211], v149 offset:23552
	global_load_lds_dwordx4 v128, s[34:35]
	s_add_i32 m0, s28, 0x2000
	s_add_u32 s28, s34, 0x40000
	s_mov_b64 s[98:99], s[34:35]
	s_addc_u32 s29, s35, 0
	s_add_i32 s59, s53, s43
	global_load_lds_dwordx4 v130, s[34:35]
	s_mov_b32 m0, s59
	s_nop 0
	global_load_lds_dwordx4 v128, s[28:29]
	s_add_i32 m0, s59, 0x2000
	s_nop 0
	global_load_lds_dwordx4 v130, s[28:29]
	s_waitcnt vmcnt(6)
	s_waitcnt lgkmcnt(0)
	s_barrier
	s_waitcnt lgkmcnt(0)
	v_mfma_f32_16x16x32_bf16 v[60:63], v[140:143], v[178:181], v[60:63]
	v_mfma_f32_16x16x32_bf16 v[56:59], v[154:157], v[178:181], v[56:59]
	v_mfma_f32_16x16x32_bf16 v[44:47], v[140:143], v[186:189], v[44:47]
	v_mfma_f32_16x16x32_bf16 v[40:43], v[154:157], v[186:189], v[40:43]
	v_mfma_f32_16x16x32_bf16 v[28:31], v[140:143], v[194:197], v[28:31]
	v_mfma_f32_16x16x32_bf16 v[24:27], v[154:157], v[194:197], v[24:27]
	v_mfma_f32_16x16x32_bf16 v[12:15], v[140:143], v[202:205], v[12:15]
	v_mfma_f32_16x16x32_bf16 v[8:11], v[154:157], v[202:205], v[8:11]
	v_mfma_f32_16x16x32_bf16 v[60:63], v[150:153], v[182:185], v[60:63]
	v_mfma_f32_16x16x32_bf16 v[56:59], v[158:161], v[182:185], v[56:59]
	v_mfma_f32_16x16x32_bf16 v[44:47], v[150:153], v[190:193], v[44:47]
	v_mfma_f32_16x16x32_bf16 v[40:43], v[158:161], v[190:193], v[40:43]
	v_mfma_f32_16x16x32_bf16 v[28:31], v[150:153], v[198:201], v[28:31]
	v_mfma_f32_16x16x32_bf16 v[24:27], v[158:161], v[198:201], v[24:27]
	v_mfma_f32_16x16x32_bf16 v[12:15], v[150:153], v[208:211], v[12:15]
	v_mfma_f32_16x16x32_bf16 v[8:11], v[158:161], v[208:211], v[8:11]
	v_mfma_f32_16x16x32_bf16 v[52:55], v[162:165], v[178:181], v[52:55]
	v_mfma_f32_16x16x32_bf16 v[48:51], v[170:173], v[178:181], v[48:51]
	v_mfma_f32_16x16x32_bf16 v[36:39], v[162:165], v[186:189], v[36:39]
	v_mfma_f32_16x16x32_bf16 v[32:35], v[170:173], v[186:189], v[32:35]
	v_mfma_f32_16x16x32_bf16 v[20:23], v[162:165], v[194:197], v[20:23]
	v_mfma_f32_16x16x32_bf16 v[16:19], v[170:173], v[194:197], v[16:19]
	v_mfma_f32_16x16x32_bf16 v[4:7], v[162:165], v[202:205], v[4:7]
	v_mfma_f32_16x16x32_bf16 v[0:3], v[170:173], v[202:205], v[0:3]
	v_mfma_f32_16x16x32_bf16 v[52:55], v[166:169], v[182:185], v[52:55]
	v_mfma_f32_16x16x32_bf16 v[48:51], v[174:177], v[182:185], v[48:51]
	v_mfma_f32_16x16x32_bf16 v[36:39], v[166:169], v[190:193], v[36:39]
	v_mfma_f32_16x16x32_bf16 v[32:35], v[174:177], v[190:193], v[32:35]
	v_mfma_f32_16x16x32_bf16 v[20:23], v[166:169], v[198:201], v[20:23]
	v_mfma_f32_16x16x32_bf16 v[16:19], v[174:177], v[198:201], v[16:19]
	v_mfma_f32_16x16x32_bf16 v[4:7], v[166:169], v[208:211], v[4:7]
	v_mfma_f32_16x16x32_bf16 v[0:3], v[174:177], v[208:211], v[0:3]
	s_barrier
	s_mov_b32 m0, s44
	s_nop 0
	global_load_lds_dwordx4 v128, s[36:37]
	s_mov_b32 m0, s45
	s_nop 0
	global_load_lds_dwordx4 v130, s[36:37]
	s_add_i32 s59, 0, 0x18000
	s_add_i32 s60, 0, 0x1c000
	s_add_u32 s28, s36, 0x40000
	s_addc_u32 s29, s37, 0
	s_mov_b32 m0, s46
	s_nop 0
	global_load_lds_dwordx4 v128, s[28:29]
	s_mov_b32 m0, s47
	s_nop 0
	global_load_lds_dwordx4 v130, s[28:29]
	v_add_u32_e32 v158, s59, v145
	v_add_u32_e32 v174, s60, v145
	ds_read_b128 v[140:143], v158
	ds_read_b128 v[150:153], v158 offset:1024
	ds_read_b128 v[154:157], v158 offset:2048
	ds_read_b128 v[158:161], v158 offset:3072
	ds_read_b128 v[162:165], v174
	ds_read_b128 v[166:169], v174 offset:1024
	ds_read_b128 v[170:173], v174 offset:2048
	ds_read_b128 v[174:177], v174 offset:3072
	ds_read_b128 v[178:181], v149 offset:32768
	ds_read_b128 v[182:185], v149 offset:33792
	ds_read_b128 v[186:189], v149 offset:34816
	ds_read_b128 v[190:193], v149 offset:35840
	ds_read_b128 v[194:197], v149 offset:36864
	ds_read_b128 v[198:201], v149 offset:37888
	ds_read_b128 v[202:205], v149 offset:38912
	ds_read_b128 v[208:211], v149 offset:39936
	s_waitcnt vmcnt(8)
	s_waitcnt lgkmcnt(0)
	s_barrier
	s_waitcnt lgkmcnt(0)
	v_mfma_f32_16x16x32_bf16 v[124:127], v[140:143], v[178:181], v[124:127]
	v_mfma_f32_16x16x32_bf16 v[120:123], v[154:157], v[178:181], v[120:123]
	v_mfma_f32_16x16x32_bf16 v[108:111], v[140:143], v[186:189], v[108:111]
	v_mfma_f32_16x16x32_bf16 v[104:107], v[154:157], v[186:189], v[104:107]
	v_mfma_f32_16x16x32_bf16 v[92:95], v[140:143], v[194:197], v[92:95]
	v_mfma_f32_16x16x32_bf16 v[88:91], v[154:157], v[194:197], v[88:91]
	v_mfma_f32_16x16x32_bf16 v[76:79], v[140:143], v[202:205], v[76:79]
	v_mfma_f32_16x16x32_bf16 v[72:75], v[154:157], v[202:205], v[72:75]
	v_mfma_f32_16x16x32_bf16 v[124:127], v[150:153], v[182:185], v[124:127]
	v_mfma_f32_16x16x32_bf16 v[120:123], v[158:161], v[182:185], v[120:123]
	v_mfma_f32_16x16x32_bf16 v[108:111], v[150:153], v[190:193], v[108:111]
	v_mfma_f32_16x16x32_bf16 v[104:107], v[158:161], v[190:193], v[104:107]
	v_mfma_f32_16x16x32_bf16 v[92:95], v[150:153], v[198:201], v[92:95]
	v_mfma_f32_16x16x32_bf16 v[88:91], v[158:161], v[198:201], v[88:91]
	v_mfma_f32_16x16x32_bf16 v[76:79], v[150:153], v[208:211], v[76:79]
	v_mfma_f32_16x16x32_bf16 v[72:75], v[158:161], v[208:211], v[72:75]
	v_mfma_f32_16x16x32_bf16 v[116:119], v[162:165], v[178:181], v[116:119]
	v_mfma_f32_16x16x32_bf16 v[112:115], v[170:173], v[178:181], v[112:115]
	v_mfma_f32_16x16x32_bf16 v[100:103], v[162:165], v[186:189], v[100:103]
	v_mfma_f32_16x16x32_bf16 v[96:99], v[170:173], v[186:189], v[96:99]
	v_mfma_f32_16x16x32_bf16 v[84:87], v[162:165], v[194:197], v[84:87]
	v_mfma_f32_16x16x32_bf16 v[80:83], v[170:173], v[194:197], v[80:83]
	v_mfma_f32_16x16x32_bf16 v[68:71], v[162:165], v[202:205], v[68:71]
	v_mfma_f32_16x16x32_bf16 v[64:67], v[170:173], v[202:205], v[64:67]
	v_mfma_f32_16x16x32_bf16 v[116:119], v[166:169], v[182:185], v[116:119]
	v_mfma_f32_16x16x32_bf16 v[112:115], v[174:177], v[182:185], v[112:115]
	v_mfma_f32_16x16x32_bf16 v[100:103], v[166:169], v[190:193], v[100:103]
	v_mfma_f32_16x16x32_bf16 v[96:99], v[174:177], v[190:193], v[96:99]
	v_mfma_f32_16x16x32_bf16 v[84:87], v[166:169], v[198:201], v[84:87]
	v_mfma_f32_16x16x32_bf16 v[80:83], v[174:177], v[198:201], v[80:83]
	v_mfma_f32_16x16x32_bf16 v[68:71], v[166:169], v[208:211], v[68:71]
	v_mfma_f32_16x16x32_bf16 v[64:67], v[174:177], v[208:211], v[64:67]
	s_barrier
	s_add_i32 s28, s59, s43
	s_mov_b32 m0, s28
	ds_read_b128 v[178:181], v149 offset:49152
	ds_read_b128 v[182:185], v149 offset:50176
	ds_read_b128 v[186:189], v149 offset:51200
	ds_read_b128 v[190:193], v149 offset:52224
	ds_read_b128 v[194:197], v149 offset:53248
	ds_read_b128 v[198:201], v149 offset:54272
	ds_read_b128 v[202:205], v149 offset:55296
	ds_read_b128 v[208:211], v149 offset:56320
	global_load_lds_dwordx4 v212, s[34:35]
	s_add_i32 m0, s28, 0x2000
	s_add_u32 s28, s34, 0x40080
	s_addc_u32 s29, s35, 0
	s_add_i32 s34, s60, s43
	global_load_lds_dwordx4 v213, s[98:99]
	s_mov_b32 m0, s34
	s_nop 0
	global_load_lds_dwordx4 v128, s[28:29]
	s_add_i32 m0, s34, 0x2000
	s_nop 0
	global_load_lds_dwordx4 v130, s[28:29]
	s_cmp_lg_u32 s58, 12
	s_cbranch_scc1 .Lbal_last_20
	s_mov_b32 m0, s49
	s_nop 0
	global_load_lds_dwordx4 v212, s[36:37]
	s_mov_b32 m0, s50
	s_nop 0
	global_load_lds_dwordx4 v213, s[36:37]

.Lbal_first_19:
	s_add_u32 s28, s26, 0xfffc0080
	s_addc_u32 s29, s27, -1
	s_cmp_eq_u32 s53, 12
	s_cselect_b32 s31, s21, s29
	s_cselect_b32 s30, s49, s28
	s_cselect_b32 s29, s19, s52
	s_cselect_b32 s28, s50, s51
	s_add_i32 m0, s39, 0xc000
	s_nop 0
	global_load_lds_dwordx4 v138, s[26:27]
	s_add_i32 m0, s39, 0xe000
	s_nop 0
	global_load_lds_dwordx4 v136, s[26:27]
	ds_read_b128 v[144:147], v151
	ds_read_b128 v[156:159], v151 offset:1024
	ds_read_b128 v[160:163], v151 offset:2048
	ds_read_b128 v[164:167], v151 offset:3072
	ds_read_b128 v[168:171], v152
	ds_read_b128 v[172:175], v152 offset:1024
	ds_read_b128 v[176:179], v152 offset:2048
	ds_read_b128 v[180:183], v152 offset:3072
	ds_read_b128 v[184:187], v153
	ds_read_b128 v[188:191], v153 offset:1024
	ds_read_b128 v[192:195], v153 offset:2048
	ds_read_b128 v[196:199], v153 offset:3072
	ds_read_b128 v[200:203], v153 offset:4096
	ds_read_b128 v[208:211], v153 offset:5120
	ds_read_b128 v[212:215], v153 offset:6144
	ds_read_b128 v[216:219], v153 offset:7168
	s_waitcnt vmcnt(8)
	s_waitcnt lgkmcnt(0)
	s_barrier
	s_waitcnt lgkmcnt(0)
	v_mfma_f32_16x16x32_bf16 v[124:127], v[144:147], v[184:187], v[124:127]
	v_mfma_f32_16x16x32_bf16 v[120:123], v[160:163], v[184:187], v[120:123]
	v_mfma_f32_16x16x32_bf16 v[108:111], v[144:147], v[192:195], v[108:111]
	v_mfma_f32_16x16x32_bf16 v[104:107], v[160:163], v[192:195], v[104:107]
	v_mfma_f32_16x16x32_bf16 v[92:95], v[144:147], v[200:203], v[92:95]
	v_mfma_f32_16x16x32_bf16 v[88:91], v[160:163], v[200:203], v[88:91]
	v_mfma_f32_16x16x32_bf16 v[76:79], v[144:147], v[212:215], v[76:79]
	v_mfma_f32_16x16x32_bf16 v[72:75], v[160:163], v[212:215], v[72:75]
	v_mfma_f32_16x16x32_bf16 v[124:127], v[156:159], v[188:191], v[124:127]
	v_mfma_f32_16x16x32_bf16 v[120:123], v[164:167], v[188:191], v[120:123]
	v_mfma_f32_16x16x32_bf16 v[108:111], v[156:159], v[196:199], v[108:111]
	v_mfma_f32_16x16x32_bf16 v[104:107], v[164:167], v[196:199], v[104:107]
	v_mfma_f32_16x16x32_bf16 v[92:95], v[156:159], v[208:211], v[92:95]
	v_mfma_f32_16x16x32_bf16 v[88:91], v[164:167], v[208:211], v[88:91]
	v_mfma_f32_16x16x32_bf16 v[76:79], v[156:159], v[216:219], v[76:79]
	v_mfma_f32_16x16x32_bf16 v[72:75], v[164:167], v[216:219], v[72:75]
	v_mfma_f32_16x16x32_bf16 v[116:119], v[168:171], v[184:187], v[116:119]
	v_mfma_f32_16x16x32_bf16 v[112:115], v[176:179], v[184:187], v[112:115]
	v_mfma_f32_16x16x32_bf16 v[100:103], v[168:171], v[192:195], v[100:103]
	v_mfma_f32_16x16x32_bf16 v[96:99], v[176:179], v[192:195], v[96:99]
	v_mfma_f32_16x16x32_bf16 v[84:87], v[168:171], v[200:203], v[84:87]
	v_mfma_f32_16x16x32_bf16 v[80:83], v[176:179], v[200:203], v[80:83]
	v_mfma_f32_16x16x32_bf16 v[68:71], v[168:171], v[212:215], v[68:71]
	v_mfma_f32_16x16x32_bf16 v[64:67], v[176:179], v[212:215], v[64:67]
	v_mfma_f32_16x16x32_bf16 v[116:119], v[172:175], v[188:191], v[116:119]
	v_mfma_f32_16x16x32_bf16 v[112:115], v[180:183], v[188:191], v[112:115]
	v_mfma_f32_16x16x32_bf16 v[100:103], v[172:175], v[196:199], v[100:103]
	v_mfma_f32_16x16x32_bf16 v[96:99], v[180:183], v[196:199], v[96:99]
	v_mfma_f32_16x16x32_bf16 v[84:87], v[172:175], v[208:211], v[84:87]
	v_mfma_f32_16x16x32_bf16 v[80:83], v[180:183], v[208:211], v[80:83]
	v_mfma_f32_16x16x32_bf16 v[68:71], v[172:175], v[216:219], v[68:71]
	v_mfma_f32_16x16x32_bf16 v[64:67], v[180:183], v[216:219], v[64:67]
	s_barrier
	s_add_i32 s54, s46, s38
	s_mov_b32 m0, s54
	ds_read_b128 v[184:187], v153 offset:16384
	ds_read_b128 v[188:191], v153 offset:17408
	ds_read_b128 v[192:195], v153 offset:18432
	ds_read_b128 v[196:199], v153 offset:19456
	ds_read_b128 v[200:203], v153 offset:20480
	ds_read_b128 v[208:211], v153 offset:21504
	ds_read_b128 v[212:215], v153 offset:22528
	ds_read_b128 v[216:219], v153 offset:23552
	global_load_lds_dwordx4 v130, s[28:29]
	s_add_i32 m0, s54, 0x2000
	s_add_u32 s54, s28, 0x40000
	s_mov_b64 s[98:99], s[28:29]
	s_addc_u32 s55, s29, 0
	s_add_i32 s56, s47, s38
	global_load_lds_dwordx4 v134, s[28:29]
	s_mov_b32 m0, s56
	s_mov_b64 s[100:101], s[30:31]
	global_load_lds_dwordx4 v130, s[54:55]
	s_add_i32 m0, s56, 0x2000
	s_nop 0
	global_load_lds_dwordx4 v134, s[54:55]
	s_waitcnt vmcnt(6)
	s_waitcnt lgkmcnt(0)
	s_barrier
	s_waitcnt lgkmcnt(0)
	v_mfma_f32_16x16x32_bf16 v[60:63], v[144:147], v[184:187], v[60:63]
	v_mfma_f32_16x16x32_bf16 v[56:59], v[160:163], v[184:187], v[56:59]
	v_mfma_f32_16x16x32_bf16 v[44:47], v[144:147], v[192:195], v[44:47]
	v_mfma_f32_16x16x32_bf16 v[40:43], v[160:163], v[192:195], v[40:43]
	v_mfma_f32_16x16x32_bf16 v[28:31], v[144:147], v[200:203], v[28:31]
	v_mfma_f32_16x16x32_bf16 v[24:27], v[160:163], v[200:203], v[24:27]
	v_mfma_f32_16x16x32_bf16 v[12:15], v[144:147], v[212:215], v[12:15]
	v_mfma_f32_16x16x32_bf16 v[8:11], v[160:163], v[212:215], v[8:11]
	v_mfma_f32_16x16x32_bf16 v[60:63], v[156:159], v[188:191], v[60:63]
	v_mfma_f32_16x16x32_bf16 v[56:59], v[164:167], v[188:191], v[56:59]
	v_mfma_f32_16x16x32_bf16 v[44:47], v[156:159], v[196:199], v[44:47]
	v_mfma_f32_16x16x32_bf16 v[40:43], v[164:167], v[196:199], v[40:43]
	v_mfma_f32_16x16x32_bf16 v[28:31], v[156:159], v[208:211], v[28:31]
	v_mfma_f32_16x16x32_bf16 v[24:27], v[164:167], v[208:211], v[24:27]
	v_mfma_f32_16x16x32_bf16 v[12:15], v[156:159], v[216:219], v[12:15]
	v_mfma_f32_16x16x32_bf16 v[8:11], v[164:167], v[216:219], v[8:11]
	v_mfma_f32_16x16x32_bf16 v[52:55], v[168:171], v[184:187], v[52:55]
	v_mfma_f32_16x16x32_bf16 v[48:51], v[176:179], v[184:187], v[48:51]
	v_mfma_f32_16x16x32_bf16 v[36:39], v[168:171], v[192:195], v[36:39]
	v_mfma_f32_16x16x32_bf16 v[32:35], v[176:179], v[192:195], v[32:35]
	v_mfma_f32_16x16x32_bf16 v[20:23], v[168:171], v[200:203], v[20:23]
	v_mfma_f32_16x16x32_bf16 v[16:19], v[176:179], v[200:203], v[16:19]
	v_mfma_f32_16x16x32_bf16 v[4:7], v[168:171], v[212:215], v[4:7]
	v_mfma_f32_16x16x32_bf16 v[0:3], v[176:179], v[212:215], v[0:3]
	v_mfma_f32_16x16x32_bf16 v[52:55], v[172:175], v[188:191], v[52:55]
	v_mfma_f32_16x16x32_bf16 v[48:51], v[180:183], v[188:191], v[48:51]
	v_mfma_f32_16x16x32_bf16 v[36:39], v[172:175], v[196:199], v[36:39]
	v_mfma_f32_16x16x32_bf16 v[32:35], v[180:183], v[196:199], v[32:35]
	v_mfma_f32_16x16x32_bf16 v[20:23], v[172:175], v[208:211], v[20:23]
	v_mfma_f32_16x16x32_bf16 v[16:19], v[180:183], v[208:211], v[16:19]
	v_mfma_f32_16x16x32_bf16 v[4:7], v[172:175], v[216:219], v[4:7]
	v_mfma_f32_16x16x32_bf16 v[0:3], v[180:183], v[216:219], v[0:3]
	s_barrier
	s_mov_b32 m0, s39
	s_nop 0
	global_load_lds_dwordx4 v128, s[30:31]
	s_mov_b32 m0, s40
	s_nop 0
	global_load_lds_dwordx4 v132, s[30:31]
	s_add_i32 s54, 0, 0x18000
	s_add_i32 s55, 0, 0x1c000
	s_add_u32 s30, s30, 0x40000
	s_addc_u32 s31, s31, 0
	s_mov_b32 m0, s41
	s_nop 0
	global_load_lds_dwordx4 v128, s[30:31]
	s_mov_b32 m0, s42
	s_nop 0
	global_load_lds_dwordx4 v132, s[30:31]
	v_add_u32_e32 v155, s54, v149
	ds_read_b128 v[144:147], v155
	ds_read_b128 v[156:159], v155 offset:1024
	ds_read_b128 v[160:163], v155 offset:2048
	ds_read_b128 v[164:167], v155 offset:3072
	v_add_u32_e32 v155, s55, v149
	ds_read_b128 v[168:171], v155
	ds_read_b128 v[172:175], v155 offset:1024
	ds_read_b128 v[176:179], v155 offset:2048
	ds_read_b128 v[180:183], v155 offset:3072
	ds_read_b128 v[184:187], v153 offset:32768
	ds_read_b128 v[188:191], v153 offset:33792
	ds_read_b128 v[192:195], v153 offset:34816
	ds_read_b128 v[196:199], v153 offset:35840
	ds_read_b128 v[200:203], v153 offset:36864
	ds_read_b128 v[208:211], v153 offset:37888
	ds_read_b128 v[212:215], v153 offset:38912
	ds_read_b128 v[216:219], v153 offset:39936
	s_waitcnt vmcnt(8)
	s_waitcnt lgkmcnt(0)
	s_barrier
	s_waitcnt lgkmcnt(0)
	v_mfma_f32_16x16x32_bf16 v[124:127], v[144:147], v[184:187], v[124:127]
	v_mfma_f32_16x16x32_bf16 v[120:123], v[160:163], v[184:187], v[120:123]
	v_mfma_f32_16x16x32_bf16 v[108:111], v[144:147], v[192:195], v[108:111]
	v_mfma_f32_16x16x32_bf16 v[104:107], v[160:163], v[192:195], v[104:107]
	v_mfma_f32_16x16x32_bf16 v[92:95], v[144:147], v[200:203], v[92:95]
	v_mfma_f32_16x16x32_bf16 v[88:91], v[160:163], v[200:203], v[88:91]
	v_mfma_f32_16x16x32_bf16 v[76:79], v[144:147], v[212:215], v[76:79]
	v_mfma_f32_16x16x32_bf16 v[72:75], v[160:163], v[212:215], v[72:75]
	v_mfma_f32_16x16x32_bf16 v[124:127], v[156:159], v[188:191], v[124:127]
	v_mfma_f32_16x16x32_bf16 v[120:123], v[164:167], v[188:191], v[120:123]
	v_mfma_f32_16x16x32_bf16 v[108:111], v[156:159], v[196:199], v[108:111]
	v_mfma_f32_16x16x32_bf16 v[104:107], v[164:167], v[196:199], v[104:107]
	v_mfma_f32_16x16x32_bf16 v[92:95], v[156:159], v[208:211], v[92:95]
	v_mfma_f32_16x16x32_bf16 v[88:91], v[164:167], v[208:211], v[88:91]
	v_mfma_f32_16x16x32_bf16 v[76:79], v[156:159], v[216:219], v[76:79]
	v_mfma_f32_16x16x32_bf16 v[72:75], v[164:167], v[216:219], v[72:75]
	v_mfma_f32_16x16x32_bf16 v[116:119], v[168:171], v[184:187], v[116:119]
	v_mfma_f32_16x16x32_bf16 v[112:115], v[176:179], v[184:187], v[112:115]
	v_mfma_f32_16x16x32_bf16 v[100:103], v[168:171], v[192:195], v[100:103]
	v_mfma_f32_16x16x32_bf16 v[96:99], v[176:179], v[192:195], v[96:99]
	v_mfma_f32_16x16x32_bf16 v[84:87], v[168:171], v[200:203], v[84:87]
	v_mfma_f32_16x16x32_bf16 v[80:83], v[176:179], v[200:203], v[80:83]
	v_mfma_f32_16x16x32_bf16 v[68:71], v[168:171], v[212:215], v[68:71]
	v_mfma_f32_16x16x32_bf16 v[64:67], v[176:179], v[212:215], v[64:67]
	v_mfma_f32_16x16x32_bf16 v[116:119], v[172:175], v[188:191], v[116:119]
	v_mfma_f32_16x16x32_bf16 v[112:115], v[180:183], v[188:191], v[112:115]
	v_mfma_f32_16x16x32_bf16 v[100:103], v[172:175], v[196:199], v[100:103]
	v_mfma_f32_16x16x32_bf16 v[96:99], v[180:183], v[196:199], v[96:99]
	v_mfma_f32_16x16x32_bf16 v[84:87], v[172:175], v[208:211], v[84:87]
	v_mfma_f32_16x16x32_bf16 v[80:83], v[180:183], v[208:211], v[80:83]
	v_mfma_f32_16x16x32_bf16 v[68:71], v[172:175], v[216:219], v[68:71]
	v_mfma_f32_16x16x32_bf16 v[64:67], v[180:183], v[216:219], v[64:67]
	s_barrier
	s_add_i32 s30, s54, s38
	s_mov_b32 m0, s30
	ds_read_b128 v[184:187], v153 offset:49152
	ds_read_b128 v[188:191], v153 offset:50176
	ds_read_b128 v[192:195], v153 offset:51200
	ds_read_b128 v[196:199], v153 offset:52224
	ds_read_b128 v[200:203], v153 offset:53248
	ds_read_b128 v[208:211], v153 offset:54272
	ds_read_b128 v[212:215], v153 offset:55296
	ds_read_b128 v[216:219], v153 offset:56320
	global_load_lds_dwordx4 v205, s[28:29]
	s_add_i32 m0, s30, 0x2000
	s_add_u32 s28, s28, 0x40080
	s_addc_u32 s29, s29, 0
	s_add_i32 s30, s55, s38
	global_load_lds_dwordx4 v221, s[98:99]
	s_mov_b32 m0, s30
	s_nop 0
	global_load_lds_dwordx4 v130, s[28:29]
	s_add_i32 m0, s30, 0x2000
	s_nop 0
	global_load_lds_dwordx4 v134, s[28:29]
	s_cmp_lg_u32 s53, 12
	s_cbranch_scc1 .Lbal_last_19
	s_mov_b32 m0, s44
	s_nop 0
	global_load_lds_dwordx4 v204, s[100:101]
	s_mov_b32 m0, s45
	s_nop 0
	global_load_lds_dwordx4 v220, s[100:101]

.Lbal_first_18:
	s_add_u32 s30, s28, 0x100
	s_addc_u32 s31, s29, 0
	s_cmp_eq_u32 s58, 60
	s_cselect_b32 s37, s21, s31
	s_cselect_b32 s36, s27, s30
	s_cselect_b32 s35, s19, s57
	s_cselect_b32 s34, s55, s56
	s_add_i32 m0, s44, 0xc000
	s_nop 0
	global_load_lds_dwordx4 v134, s[28:29]
	s_add_i32 m0, s44, 0xe000
	s_nop 0
	global_load_lds_dwordx4 v132, s[28:29]
	ds_read_b128 v[140:143], v147
	ds_read_b128 v[150:153], v147 offset:1024
	ds_read_b128 v[154:157], v147 offset:2048
	ds_read_b128 v[158:161], v147 offset:3072
	ds_read_b128 v[162:165], v148
	ds_read_b128 v[166:169], v148 offset:1024
	ds_read_b128 v[170:173], v148 offset:2048
	ds_read_b128 v[174:177], v148 offset:3072
	ds_read_b128 v[178:181], v149
	ds_read_b128 v[182:185], v149 offset:1024
	ds_read_b128 v[186:189], v149 offset:2048
	ds_read_b128 v[190:193], v149 offset:3072
	ds_read_b128 v[194:197], v149 offset:4096
	ds_read_b128 v[198:201], v149 offset:5120
	ds_read_b128 v[202:205], v149 offset:6144
	ds_read_b128 v[208:211], v149 offset:7168
	s_waitcnt vmcnt(8)
	s_waitcnt lgkmcnt(0)
	s_barrier
	s_waitcnt lgkmcnt(0)
	v_mfma_f32_16x16x32_bf16 v[124:127], v[140:143], v[178:181], v[124:127]
	v_mfma_f32_16x16x32_bf16 v[120:123], v[154:157], v[178:181], v[120:123]
	v_mfma_f32_16x16x32_bf16 v[108:111], v[140:143], v[186:189], v[108:111]
	v_mfma_f32_16x16x32_bf16 v[104:107], v[154:157], v[186:189], v[104:107]
	v_mfma_f32_16x16x32_bf16 v[92:95], v[140:143], v[194:197], v[92:95]
	v_mfma_f32_16x16x32_bf16 v[88:91], v[154:157], v[194:197], v[88:91]
	v_mfma_f32_16x16x32_bf16 v[76:79], v[140:143], v[202:205], v[76:79]
	v_mfma_f32_16x16x32_bf16 v[72:75], v[154:157], v[202:205], v[72:75]
	v_mfma_f32_16x16x32_bf16 v[124:127], v[150:153], v[182:185], v[124:127]
	v_mfma_f32_16x16x32_bf16 v[120:123], v[158:161], v[182:185], v[120:123]
	v_mfma_f32_16x16x32_bf16 v[108:111], v[150:153], v[190:193], v[108:111]
	v_mfma_f32_16x16x32_bf16 v[104:107], v[158:161], v[190:193], v[104:107]
	v_mfma_f32_16x16x32_bf16 v[92:95], v[150:153], v[198:201], v[92:95]
	v_mfma_f32_16x16x32_bf16 v[88:91], v[158:161], v[198:201], v[88:91]
	v_mfma_f32_16x16x32_bf16 v[76:79], v[150:153], v[208:211], v[76:79]
	v_mfma_f32_16x16x32_bf16 v[72:75], v[158:161], v[208:211], v[72:75]
	v_mfma_f32_16x16x32_bf16 v[116:119], v[162:165], v[178:181], v[116:119]
	v_mfma_f32_16x16x32_bf16 v[112:115], v[170:173], v[178:181], v[112:115]
	v_mfma_f32_16x16x32_bf16 v[100:103], v[162:165], v[186:189], v[100:103]
	v_mfma_f32_16x16x32_bf16 v[96:99], v[170:173], v[186:189], v[96:99]
	v_mfma_f32_16x16x32_bf16 v[84:87], v[162:165], v[194:197], v[84:87]
	v_mfma_f32_16x16x32_bf16 v[80:83], v[170:173], v[194:197], v[80:83]
	v_mfma_f32_16x16x32_bf16 v[68:71], v[162:165], v[202:205], v[68:71]
	v_mfma_f32_16x16x32_bf16 v[64:67], v[170:173], v[202:205], v[64:67]
	v_mfma_f32_16x16x32_bf16 v[116:119], v[166:169], v[182:185], v[116:119]
	v_mfma_f32_16x16x32_bf16 v[112:115], v[174:177], v[182:185], v[112:115]
	v_mfma_f32_16x16x32_bf16 v[100:103], v[166:169], v[190:193], v[100:103]
	v_mfma_f32_16x16x32_bf16 v[96:99], v[174:177], v[190:193], v[96:99]
	v_mfma_f32_16x16x32_bf16 v[84:87], v[166:169], v[198:201], v[84:87]
	v_mfma_f32_16x16x32_bf16 v[80:83], v[174:177], v[198:201], v[80:83]
	v_mfma_f32_16x16x32_bf16 v[68:71], v[166:169], v[208:211], v[68:71]
	v_mfma_f32_16x16x32_bf16 v[64:67], v[174:177], v[208:211], v[64:67]
	s_barrier
	s_add_i32 s28, s52, s43
	s_mov_b32 m0, s28
	ds_read_b128 v[178:181], v149 offset:16384
	ds_read_b128 v[182:185], v149 offset:17408
	ds_read_b128 v[186:189], v149 offset:18432
	ds_read_b128 v[190:193], v149 offset:19456
	ds_read_b128 v[194:197], v149 offset:20480
	ds_read_b128 v[198:201], v149 offset:21504
	ds_read_b128 v[202:205], v149 offset:22528
	ds_read_b128 v[208:211], v149 offset:23552
	global_load_lds_dwordx4 v128, s[34:35]
	s_add_i32 m0, s28, 0x2000
	s_add_u32 s28, s34, 0x100000
	s_mov_b64 s[98:99], s[34:35]
	s_addc_u32 s29, s35, 0
	s_add_i32 s59, s53, s43
	global_load_lds_dwordx4 v130, s[34:35]
	s_mov_b32 m0, s59
	s_nop 0
	global_load_lds_dwordx4 v128, s[28:29]
	s_add_i32 m0, s59, 0x2000
	s_nop 0
	global_load_lds_dwordx4 v130, s[28:29]
	s_waitcnt vmcnt(6)
	s_waitcnt lgkmcnt(0)
	s_barrier
	s_waitcnt lgkmcnt(0)
	v_mfma_f32_16x16x32_bf16 v[60:63], v[140:143], v[178:181], v[60:63]
	v_mfma_f32_16x16x32_bf16 v[56:59], v[154:157], v[178:181], v[56:59]
	v_mfma_f32_16x16x32_bf16 v[44:47], v[140:143], v[186:189], v[44:47]
	v_mfma_f32_16x16x32_bf16 v[40:43], v[154:157], v[186:189], v[40:43]
	v_mfma_f32_16x16x32_bf16 v[28:31], v[140:143], v[194:197], v[28:31]
	v_mfma_f32_16x16x32_bf16 v[24:27], v[154:157], v[194:197], v[24:27]
	v_mfma_f32_16x16x32_bf16 v[12:15], v[140:143], v[202:205], v[12:15]
	v_mfma_f32_16x16x32_bf16 v[8:11], v[154:157], v[202:205], v[8:11]
	v_mfma_f32_16x16x32_bf16 v[60:63], v[150:153], v[182:185], v[60:63]
	v_mfma_f32_16x16x32_bf16 v[56:59], v[158:161], v[182:185], v[56:59]
	v_mfma_f32_16x16x32_bf16 v[44:47], v[150:153], v[190:193], v[44:47]
	v_mfma_f32_16x16x32_bf16 v[40:43], v[158:161], v[190:193], v[40:43]
	v_mfma_f32_16x16x32_bf16 v[28:31], v[150:153], v[198:201], v[28:31]
	v_mfma_f32_16x16x32_bf16 v[24:27], v[158:161], v[198:201], v[24:27]
	v_mfma_f32_16x16x32_bf16 v[12:15], v[150:153], v[208:211], v[12:15]
	v_mfma_f32_16x16x32_bf16 v[8:11], v[158:161], v[208:211], v[8:11]
	v_mfma_f32_16x16x32_bf16 v[52:55], v[162:165], v[178:181], v[52:55]
	v_mfma_f32_16x16x32_bf16 v[48:51], v[170:173], v[178:181], v[48:51]
	v_mfma_f32_16x16x32_bf16 v[36:39], v[162:165], v[186:189], v[36:39]
	v_mfma_f32_16x16x32_bf16 v[32:35], v[170:173], v[186:189], v[32:35]
	v_mfma_f32_16x16x32_bf16 v[20:23], v[162:165], v[194:197], v[20:23]
	v_mfma_f32_16x16x32_bf16 v[16:19], v[170:173], v[194:197], v[16:19]
	v_mfma_f32_16x16x32_bf16 v[4:7], v[162:165], v[202:205], v[4:7]
	v_mfma_f32_16x16x32_bf16 v[0:3], v[170:173], v[202:205], v[0:3]
	v_mfma_f32_16x16x32_bf16 v[52:55], v[166:169], v[182:185], v[52:55]
	v_mfma_f32_16x16x32_bf16 v[48:51], v[174:177], v[182:185], v[48:51]
	v_mfma_f32_16x16x32_bf16 v[36:39], v[166:169], v[190:193], v[36:39]
	v_mfma_f32_16x16x32_bf16 v[32:35], v[174:177], v[190:193], v[32:35]
	v_mfma_f32_16x16x32_bf16 v[20:23], v[166:169], v[198:201], v[20:23]
	v_mfma_f32_16x16x32_bf16 v[16:19], v[174:177], v[198:201], v[16:19]
	v_mfma_f32_16x16x32_bf16 v[4:7], v[166:169], v[208:211], v[4:7]
	v_mfma_f32_16x16x32_bf16 v[0:3], v[174:177], v[208:211], v[0:3]
	s_barrier
	s_mov_b32 m0, s44
	s_nop 0
	global_load_lds_dwordx4 v128, s[36:37]
	s_mov_b32 m0, s45
	s_nop 0
	global_load_lds_dwordx4 v130, s[36:37]
	s_add_i32 s59, 0, 0x18000
	s_add_i32 s60, 0, 0x1c000
	s_add_u32 s28, s36, 0x100000
	s_addc_u32 s29, s37, 0
	s_mov_b32 m0, s46
	s_nop 0
	global_load_lds_dwordx4 v128, s[28:29]
	s_mov_b32 m0, s47
	s_nop 0
	global_load_lds_dwordx4 v130, s[28:29]
	v_add_u32_e32 v158, s59, v145
	v_add_u32_e32 v174, s60, v145
	ds_read_b128 v[140:143], v158
	ds_read_b128 v[150:153], v158 offset:1024
	ds_read_b128 v[154:157], v158 offset:2048
	ds_read_b128 v[158:161], v158 offset:3072
	ds_read_b128 v[162:165], v174
	ds_read_b128 v[166:169], v174 offset:1024
	ds_read_b128 v[170:173], v174 offset:2048
	ds_read_b128 v[174:177], v174 offset:3072
	ds_read_b128 v[178:181], v149 offset:32768
	ds_read_b128 v[182:185], v149 offset:33792
	ds_read_b128 v[186:189], v149 offset:34816
	ds_read_b128 v[190:193], v149 offset:35840
	ds_read_b128 v[194:197], v149 offset:36864
	ds_read_b128 v[198:201], v149 offset:37888
	ds_read_b128 v[202:205], v149 offset:38912
	ds_read_b128 v[208:211], v149 offset:39936
	s_waitcnt vmcnt(8)
	s_waitcnt lgkmcnt(0)
	s_barrier
	s_waitcnt lgkmcnt(0)
	v_mfma_f32_16x16x32_bf16 v[124:127], v[140:143], v[178:181], v[124:127]
	v_mfma_f32_16x16x32_bf16 v[120:123], v[154:157], v[178:181], v[120:123]
	v_mfma_f32_16x16x32_bf16 v[108:111], v[140:143], v[186:189], v[108:111]
	v_mfma_f32_16x16x32_bf16 v[104:107], v[154:157], v[186:189], v[104:107]
	v_mfma_f32_16x16x32_bf16 v[92:95], v[140:143], v[194:197], v[92:95]
	v_mfma_f32_16x16x32_bf16 v[88:91], v[154:157], v[194:197], v[88:91]
	v_mfma_f32_16x16x32_bf16 v[76:79], v[140:143], v[202:205], v[76:79]
	v_mfma_f32_16x16x32_bf16 v[72:75], v[154:157], v[202:205], v[72:75]
	v_mfma_f32_16x16x32_bf16 v[124:127], v[150:153], v[182:185], v[124:127]
	v_mfma_f32_16x16x32_bf16 v[120:123], v[158:161], v[182:185], v[120:123]
	v_mfma_f32_16x16x32_bf16 v[108:111], v[150:153], v[190:193], v[108:111]
	v_mfma_f32_16x16x32_bf16 v[104:107], v[158:161], v[190:193], v[104:107]
	v_mfma_f32_16x16x32_bf16 v[92:95], v[150:153], v[198:201], v[92:95]
	v_mfma_f32_16x16x32_bf16 v[88:91], v[158:161], v[198:201], v[88:91]
	v_mfma_f32_16x16x32_bf16 v[76:79], v[150:153], v[208:211], v[76:79]
	v_mfma_f32_16x16x32_bf16 v[72:75], v[158:161], v[208:211], v[72:75]
	v_mfma_f32_16x16x32_bf16 v[116:119], v[162:165], v[178:181], v[116:119]
	v_mfma_f32_16x16x32_bf16 v[112:115], v[170:173], v[178:181], v[112:115]
	v_mfma_f32_16x16x32_bf16 v[100:103], v[162:165], v[186:189], v[100:103]
	v_mfma_f32_16x16x32_bf16 v[96:99], v[170:173], v[186:189], v[96:99]
	v_mfma_f32_16x16x32_bf16 v[84:87], v[162:165], v[194:197], v[84:87]
	v_mfma_f32_16x16x32_bf16 v[80:83], v[170:173], v[194:197], v[80:83]
	v_mfma_f32_16x16x32_bf16 v[68:71], v[162:165], v[202:205], v[68:71]
	v_mfma_f32_16x16x32_bf16 v[64:67], v[170:173], v[202:205], v[64:67]
	v_mfma_f32_16x16x32_bf16 v[116:119], v[166:169], v[182:185], v[116:119]
	v_mfma_f32_16x16x32_bf16 v[112:115], v[174:177], v[182:185], v[112:115]
	v_mfma_f32_16x16x32_bf16 v[100:103], v[166:169], v[190:193], v[100:103]
	v_mfma_f32_16x16x32_bf16 v[96:99], v[174:177], v[190:193], v[96:99]
	v_mfma_f32_16x16x32_bf16 v[84:87], v[166:169], v[198:201], v[84:87]
	v_mfma_f32_16x16x32_bf16 v[80:83], v[174:177], v[198:201], v[80:83]
	v_mfma_f32_16x16x32_bf16 v[68:71], v[166:169], v[208:211], v[68:71]
	v_mfma_f32_16x16x32_bf16 v[64:67], v[174:177], v[208:211], v[64:67]
	s_barrier
	s_add_i32 s28, s59, s43
	s_mov_b32 m0, s28
	ds_read_b128 v[178:181], v149 offset:49152
	ds_read_b128 v[182:185], v149 offset:50176
	ds_read_b128 v[186:189], v149 offset:51200
	ds_read_b128 v[190:193], v149 offset:52224
	ds_read_b128 v[194:197], v149 offset:53248
	ds_read_b128 v[198:201], v149 offset:54272
	ds_read_b128 v[202:205], v149 offset:55296
	ds_read_b128 v[208:211], v149 offset:56320
	global_load_lds_dwordx4 v212, s[34:35]
	s_add_i32 m0, s28, 0x2000
	s_add_u32 s28, s34, 0x100080
	s_addc_u32 s29, s35, 0
	s_add_i32 s34, s60, s43
	global_load_lds_dwordx4 v213, s[98:99]
	s_mov_b32 m0, s34
	s_nop 0
	global_load_lds_dwordx4 v128, s[28:29]
	s_add_i32 m0, s34, 0x2000
	s_nop 0
	global_load_lds_dwordx4 v130, s[28:29]
	s_cmp_lg_u32 s58, 60
	s_cbranch_scc1 .Lbal_last_18
	s_mov_b32 m0, s49
	s_nop 0
	global_load_lds_dwordx4 v212, s[36:37]
	s_mov_b32 m0, s50
	s_nop 0
	global_load_lds_dwordx4 v213, s[36:37]

.Lbal_first_17:
	s_add_u32 s38, s36, 0xfffc0080
	s_addc_u32 s39, s37, -1
	s_cmp_eq_u32 s61, 12
	s_cselect_b32 s41, s3, s39
	s_cselect_b32 s40, s29, s38
	s_cselect_b32 s39, s27, s60
	s_cselect_b32 s38, s58, s59
	s_add_i32 m0, s46, 0xc000
	s_nop 0
	global_load_lds_dwordx4 v134, s[36:37]
	s_add_i32 m0, s46, 0xe000
	s_nop 0
	global_load_lds_dwordx4 v132, s[36:37]
	ds_read_b128 v[140:143], v153
	ds_read_b128 v[144:147], v153 offset:1024
	ds_read_b128 v[158:161], v153 offset:2048
	ds_read_b128 v[162:165], v153 offset:3072
	ds_read_b128 v[166:169], v154
	ds_read_b128 v[170:173], v154 offset:1024
	ds_read_b128 v[174:177], v154 offset:2048
	ds_read_b128 v[178:181], v154 offset:3072
	ds_read_b128 v[182:185], v155
	ds_read_b128 v[186:189], v155 offset:1024
	ds_read_b128 v[190:193], v155 offset:2048
	ds_read_b128 v[194:197], v155 offset:3072
	ds_read_b128 v[198:201], v155 offset:4096
	ds_read_b128 v[202:205], v155 offset:5120
	ds_read_b128 v[208:211], v155 offset:6144
	ds_read_b128 v[212:215], v155 offset:7168
	s_waitcnt vmcnt(8)
	s_waitcnt lgkmcnt(0)
	s_barrier
	s_waitcnt lgkmcnt(0)
	v_mfma_f32_16x16x32_bf16 v[124:127], v[140:143], v[182:185], v[124:127]
	v_mfma_f32_16x16x32_bf16 v[120:123], v[158:161], v[182:185], v[120:123]
	v_mfma_f32_16x16x32_bf16 v[108:111], v[140:143], v[190:193], v[108:111]
	v_mfma_f32_16x16x32_bf16 v[104:107], v[158:161], v[190:193], v[104:107]
	v_mfma_f32_16x16x32_bf16 v[92:95], v[140:143], v[198:201], v[92:95]
	v_mfma_f32_16x16x32_bf16 v[88:91], v[158:161], v[198:201], v[88:91]
	v_mfma_f32_16x16x32_bf16 v[76:79], v[140:143], v[208:211], v[76:79]
	v_mfma_f32_16x16x32_bf16 v[72:75], v[158:161], v[208:211], v[72:75]
	v_mfma_f32_16x16x32_bf16 v[124:127], v[144:147], v[186:189], v[124:127]
	v_mfma_f32_16x16x32_bf16 v[120:123], v[162:165], v[186:189], v[120:123]
	v_mfma_f32_16x16x32_bf16 v[108:111], v[144:147], v[194:197], v[108:111]
	v_mfma_f32_16x16x32_bf16 v[104:107], v[162:165], v[194:197], v[104:107]
	v_mfma_f32_16x16x32_bf16 v[92:95], v[144:147], v[202:205], v[92:95]
	v_mfma_f32_16x16x32_bf16 v[88:91], v[162:165], v[202:205], v[88:91]
	v_mfma_f32_16x16x32_bf16 v[76:79], v[144:147], v[212:215], v[76:79]
	v_mfma_f32_16x16x32_bf16 v[72:75], v[162:165], v[212:215], v[72:75]
	v_mfma_f32_16x16x32_bf16 v[116:119], v[166:169], v[182:185], v[116:119]
	v_mfma_f32_16x16x32_bf16 v[112:115], v[174:177], v[182:185], v[112:115]
	v_mfma_f32_16x16x32_bf16 v[100:103], v[166:169], v[190:193], v[100:103]
	v_mfma_f32_16x16x32_bf16 v[96:99], v[174:177], v[190:193], v[96:99]
	v_mfma_f32_16x16x32_bf16 v[84:87], v[166:169], v[198:201], v[84:87]
	v_mfma_f32_16x16x32_bf16 v[80:83], v[174:177], v[198:201], v[80:83]
	v_mfma_f32_16x16x32_bf16 v[68:71], v[166:169], v[208:211], v[68:71]
	v_mfma_f32_16x16x32_bf16 v[64:67], v[174:177], v[208:211], v[64:67]
	v_mfma_f32_16x16x32_bf16 v[116:119], v[170:173], v[186:189], v[116:119]
	v_mfma_f32_16x16x32_bf16 v[112:115], v[178:181], v[186:189], v[112:115]
	v_mfma_f32_16x16x32_bf16 v[100:103], v[170:173], v[194:197], v[100:103]
	v_mfma_f32_16x16x32_bf16 v[96:99], v[178:181], v[194:197], v[96:99]
	v_mfma_f32_16x16x32_bf16 v[84:87], v[170:173], v[202:205], v[84:87]
	v_mfma_f32_16x16x32_bf16 v[80:83], v[178:181], v[202:205], v[80:83]
	v_mfma_f32_16x16x32_bf16 v[68:71], v[170:173], v[212:215], v[68:71]
	v_mfma_f32_16x16x32_bf16 v[64:67], v[178:181], v[212:215], v[64:67]
	s_barrier
	s_add_i32 s62, s54, s45
	s_mov_b32 m0, s62
	ds_read_b128 v[182:185], v155 offset:16384
	ds_read_b128 v[186:189], v155 offset:17408
	ds_read_b128 v[190:193], v155 offset:18432
	ds_read_b128 v[194:197], v155 offset:19456
	ds_read_b128 v[198:201], v155 offset:20480
	ds_read_b128 v[202:205], v155 offset:21504
	ds_read_b128 v[208:211], v155 offset:22528
	ds_read_b128 v[212:215], v155 offset:23552
	global_load_lds_dwordx4 v128, s[38:39]
	s_add_i32 m0, s62, 0x2000
	s_add_u32 s62, s38, 0x40000
	s_mov_b64 s[98:99], s[38:39]
	s_addc_u32 s63, s39, 0
	s_add_i32 s64, s55, s45
	global_load_lds_dwordx4 v130, s[38:39]
	s_mov_b32 m0, s64
	s_mov_b64 s[100:101], s[40:41]
	global_load_lds_dwordx4 v128, s[62:63]
	s_add_i32 m0, s64, 0x2000
	s_nop 0
	global_load_lds_dwordx4 v130, s[62:63]
	s_waitcnt vmcnt(6)
	s_waitcnt lgkmcnt(0)
	s_barrier
	s_waitcnt lgkmcnt(0)
	v_mfma_f32_16x16x32_bf16 v[60:63], v[140:143], v[182:185], v[60:63]
	v_mfma_f32_16x16x32_bf16 v[56:59], v[158:161], v[182:185], v[56:59]
	v_mfma_f32_16x16x32_bf16 v[44:47], v[140:143], v[190:193], v[44:47]
	v_mfma_f32_16x16x32_bf16 v[40:43], v[158:161], v[190:193], v[40:43]
	v_mfma_f32_16x16x32_bf16 v[28:31], v[140:143], v[198:201], v[28:31]
	v_mfma_f32_16x16x32_bf16 v[24:27], v[158:161], v[198:201], v[24:27]
	v_mfma_f32_16x16x32_bf16 v[12:15], v[140:143], v[208:211], v[12:15]
	v_mfma_f32_16x16x32_bf16 v[8:11], v[158:161], v[208:211], v[8:11]
	v_mfma_f32_16x16x32_bf16 v[60:63], v[144:147], v[186:189], v[60:63]
	v_mfma_f32_16x16x32_bf16 v[56:59], v[162:165], v[186:189], v[56:59]
	v_mfma_f32_16x16x32_bf16 v[44:47], v[144:147], v[194:197], v[44:47]
	v_mfma_f32_16x16x32_bf16 v[40:43], v[162:165], v[194:197], v[40:43]
	v_mfma_f32_16x16x32_bf16 v[28:31], v[144:147], v[202:205], v[28:31]
	v_mfma_f32_16x16x32_bf16 v[24:27], v[162:165], v[202:205], v[24:27]
	v_mfma_f32_16x16x32_bf16 v[12:15], v[144:147], v[212:215], v[12:15]
	v_mfma_f32_16x16x32_bf16 v[8:11], v[162:165], v[212:215], v[8:11]
	v_mfma_f32_16x16x32_bf16 v[52:55], v[166:169], v[182:185], v[52:55]
	v_mfma_f32_16x16x32_bf16 v[48:51], v[174:177], v[182:185], v[48:51]
	v_mfma_f32_16x16x32_bf16 v[36:39], v[166:169], v[190:193], v[36:39]
	v_mfma_f32_16x16x32_bf16 v[32:35], v[174:177], v[190:193], v[32:35]
	v_mfma_f32_16x16x32_bf16 v[20:23], v[166:169], v[198:201], v[20:23]
	v_mfma_f32_16x16x32_bf16 v[16:19], v[174:177], v[198:201], v[16:19]
	v_mfma_f32_16x16x32_bf16 v[4:7], v[166:169], v[208:211], v[4:7]
	v_mfma_f32_16x16x32_bf16 v[0:3], v[174:177], v[208:211], v[0:3]
	v_mfma_f32_16x16x32_bf16 v[52:55], v[170:173], v[186:189], v[52:55]
	v_mfma_f32_16x16x32_bf16 v[48:51], v[178:181], v[186:189], v[48:51]
	v_mfma_f32_16x16x32_bf16 v[36:39], v[170:173], v[194:197], v[36:39]
	v_mfma_f32_16x16x32_bf16 v[32:35], v[178:181], v[194:197], v[32:35]
	v_mfma_f32_16x16x32_bf16 v[20:23], v[170:173], v[202:205], v[20:23]
	v_mfma_f32_16x16x32_bf16 v[16:19], v[178:181], v[202:205], v[16:19]
	v_mfma_f32_16x16x32_bf16 v[4:7], v[170:173], v[212:215], v[4:7]
	v_mfma_f32_16x16x32_bf16 v[0:3], v[178:181], v[212:215], v[0:3]
	s_barrier
	s_mov_b32 m0, s46
	s_nop 0
	global_load_lds_dwordx4 v128, s[40:41]
	s_mov_b32 m0, s47
	s_nop 0
	global_load_lds_dwordx4 v130, s[40:41]
	s_add_i32 s62, 0, 0x18000
	s_add_i32 s63, 0, 0x1c000
	s_add_u32 s40, s40, 0x40000
	s_addc_u32 s41, s41, 0
	s_mov_b32 m0, s48
	s_nop 0
	global_load_lds_dwordx4 v128, s[40:41]
	s_mov_b32 m0, s49
	s_nop 0
	global_load_lds_dwordx4 v130, s[40:41]
	v_add_u32_e32 v157, s62, v151
	ds_read_b128 v[140:143], v157
	ds_read_b128 v[144:147], v157 offset:1024
	ds_read_b128 v[158:161], v157 offset:2048
	ds_read_b128 v[162:165], v157 offset:3072
	v_add_u32_e32 v157, s63, v151
	ds_read_b128 v[166:169], v157
	ds_read_b128 v[170:173], v157 offset:1024
	ds_read_b128 v[174:177], v157 offset:2048
	ds_read_b128 v[178:181], v157 offset:3072
	ds_read_b128 v[182:185], v155 offset:32768
	ds_read_b128 v[186:189], v155 offset:33792
	ds_read_b128 v[190:193], v155 offset:34816
	ds_read_b128 v[194:197], v155 offset:35840
	ds_read_b128 v[198:201], v155 offset:36864
	ds_read_b128 v[202:205], v155 offset:37888
	ds_read_b128 v[208:211], v155 offset:38912
	ds_read_b128 v[212:215], v155 offset:39936
	s_waitcnt vmcnt(8)
	s_waitcnt lgkmcnt(0)
	s_barrier
	s_waitcnt lgkmcnt(0)
	v_mfma_f32_16x16x32_bf16 v[124:127], v[140:143], v[182:185], v[124:127]
	v_mfma_f32_16x16x32_bf16 v[120:123], v[158:161], v[182:185], v[120:123]
	v_mfma_f32_16x16x32_bf16 v[108:111], v[140:143], v[190:193], v[108:111]
	v_mfma_f32_16x16x32_bf16 v[104:107], v[158:161], v[190:193], v[104:107]
	v_mfma_f32_16x16x32_bf16 v[92:95], v[140:143], v[198:201], v[92:95]
	v_mfma_f32_16x16x32_bf16 v[88:91], v[158:161], v[198:201], v[88:91]
	v_mfma_f32_16x16x32_bf16 v[76:79], v[140:143], v[208:211], v[76:79]
	v_mfma_f32_16x16x32_bf16 v[72:75], v[158:161], v[208:211], v[72:75]
	v_mfma_f32_16x16x32_bf16 v[124:127], v[144:147], v[186:189], v[124:127]
	v_mfma_f32_16x16x32_bf16 v[120:123], v[162:165], v[186:189], v[120:123]
	v_mfma_f32_16x16x32_bf16 v[108:111], v[144:147], v[194:197], v[108:111]
	v_mfma_f32_16x16x32_bf16 v[104:107], v[162:165], v[194:197], v[104:107]
	v_mfma_f32_16x16x32_bf16 v[92:95], v[144:147], v[202:205], v[92:95]
	v_mfma_f32_16x16x32_bf16 v[88:91], v[162:165], v[202:205], v[88:91]
	v_mfma_f32_16x16x32_bf16 v[76:79], v[144:147], v[212:215], v[76:79]
	v_mfma_f32_16x16x32_bf16 v[72:75], v[162:165], v[212:215], v[72:75]
	v_mfma_f32_16x16x32_bf16 v[116:119], v[166:169], v[182:185], v[116:119]
	v_mfma_f32_16x16x32_bf16 v[112:115], v[174:177], v[182:185], v[112:115]
	v_mfma_f32_16x16x32_bf16 v[100:103], v[166:169], v[190:193], v[100:103]
	v_mfma_f32_16x16x32_bf16 v[96:99], v[174:177], v[190:193], v[96:99]
	v_mfma_f32_16x16x32_bf16 v[84:87], v[166:169], v[198:201], v[84:87]
	v_mfma_f32_16x16x32_bf16 v[80:83], v[174:177], v[198:201], v[80:83]
	v_mfma_f32_16x16x32_bf16 v[68:71], v[166:169], v[208:211], v[68:71]
	v_mfma_f32_16x16x32_bf16 v[64:67], v[174:177], v[208:211], v[64:67]
	v_mfma_f32_16x16x32_bf16 v[116:119], v[170:173], v[186:189], v[116:119]
	v_mfma_f32_16x16x32_bf16 v[112:115], v[178:181], v[186:189], v[112:115]
	v_mfma_f32_16x16x32_bf16 v[100:103], v[170:173], v[194:197], v[100:103]
	v_mfma_f32_16x16x32_bf16 v[96:99], v[178:181], v[194:197], v[96:99]
	v_mfma_f32_16x16x32_bf16 v[84:87], v[170:173], v[202:205], v[84:87]
	v_mfma_f32_16x16x32_bf16 v[80:83], v[178:181], v[202:205], v[80:83]
	v_mfma_f32_16x16x32_bf16 v[68:71], v[170:173], v[212:215], v[68:71]
	v_mfma_f32_16x16x32_bf16 v[64:67], v[178:181], v[212:215], v[64:67]
	s_barrier
	s_add_i32 s40, s62, s45
	s_mov_b32 m0, s40
	ds_read_b128 v[182:185], v155 offset:49152
	ds_read_b128 v[186:189], v155 offset:50176
	ds_read_b128 v[190:193], v155 offset:51200
	ds_read_b128 v[194:197], v155 offset:52224
	ds_read_b128 v[198:201], v155 offset:53248
	ds_read_b128 v[202:205], v155 offset:54272
	ds_read_b128 v[208:211], v155 offset:55296
	ds_read_b128 v[212:215], v155 offset:56320
	global_load_lds_dwordx4 v148, s[38:39]
	s_add_i32 m0, s40, 0x2000
	s_add_u32 s38, s38, 0x40080
	s_addc_u32 s39, s39, 0
	s_add_i32 s40, s63, s45
	global_load_lds_dwordx4 v149, s[98:99]
	s_mov_b32 m0, s40
	s_nop 0
	global_load_lds_dwordx4 v128, s[38:39]
	s_add_i32 m0, s40, 0x2000
	s_nop 0
	global_load_lds_dwordx4 v130, s[38:39]
	s_cmp_lg_u32 s61, 12
	s_cbranch_scc1 .Lbal_last_17
	s_mov_b32 m0, s51
	s_nop 0
	global_load_lds_dwordx4 v148, s[100:101]
	s_mov_b32 m0, s52
	s_nop 0
	global_load_lds_dwordx4 v149, s[100:101]

.Lbal_first_16:
	s_add_u32 s26, s6, 0xfffc0080
	s_addc_u32 s27, s7, -1
	s_cmp_eq_u32 s53, 12
	s_cselect_b32 s29, s19, s27
	s_cselect_b32 s28, s49, s26
	s_cselect_b32 s27, s17, s52
	s_cselect_b32 s26, s50, s51
	s_add_i32 m0, s25, 0xc000
	s_nop 0
	global_load_lds_dwordx4 v138, s[6:7]
	s_add_i32 m0, s25, 0xe000
	s_nop 0
	global_load_lds_dwordx4 v136, s[6:7]
	ds_read_b128 v[144:147], v151
	ds_read_b128 v[156:159], v151 offset:1024
	ds_read_b128 v[160:163], v151 offset:2048
	ds_read_b128 v[164:167], v151 offset:3072
	ds_read_b128 v[168:171], v152
	ds_read_b128 v[172:175], v152 offset:1024
	ds_read_b128 v[176:179], v152 offset:2048
	ds_read_b128 v[180:183], v152 offset:3072
	ds_read_b128 v[184:187], v153
	ds_read_b128 v[188:191], v153 offset:1024
	ds_read_b128 v[192:195], v153 offset:2048
	ds_read_b128 v[196:199], v153 offset:3072
	ds_read_b128 v[200:203], v153 offset:4096
	ds_read_b128 v[208:211], v153 offset:5120
	ds_read_b128 v[212:215], v153 offset:6144
	ds_read_b128 v[216:219], v153 offset:7168
	s_waitcnt vmcnt(8)
	s_waitcnt lgkmcnt(0)
	s_barrier
	s_waitcnt lgkmcnt(0)
	v_mfma_f32_16x16x32_bf16 v[124:127], v[144:147], v[184:187], v[124:127]
	v_mfma_f32_16x16x32_bf16 v[120:123], v[160:163], v[184:187], v[120:123]
	v_mfma_f32_16x16x32_bf16 v[108:111], v[144:147], v[192:195], v[108:111]
	v_mfma_f32_16x16x32_bf16 v[104:107], v[160:163], v[192:195], v[104:107]
	v_mfma_f32_16x16x32_bf16 v[92:95], v[144:147], v[200:203], v[92:95]
	v_mfma_f32_16x16x32_bf16 v[88:91], v[160:163], v[200:203], v[88:91]
	v_mfma_f32_16x16x32_bf16 v[76:79], v[144:147], v[212:215], v[76:79]
	v_mfma_f32_16x16x32_bf16 v[72:75], v[160:163], v[212:215], v[72:75]
	v_mfma_f32_16x16x32_bf16 v[124:127], v[156:159], v[188:191], v[124:127]
	v_mfma_f32_16x16x32_bf16 v[120:123], v[164:167], v[188:191], v[120:123]
	v_mfma_f32_16x16x32_bf16 v[108:111], v[156:159], v[196:199], v[108:111]
	v_mfma_f32_16x16x32_bf16 v[104:107], v[164:167], v[196:199], v[104:107]
	v_mfma_f32_16x16x32_bf16 v[92:95], v[156:159], v[208:211], v[92:95]
	v_mfma_f32_16x16x32_bf16 v[88:91], v[164:167], v[208:211], v[88:91]
	v_mfma_f32_16x16x32_bf16 v[76:79], v[156:159], v[216:219], v[76:79]
	v_mfma_f32_16x16x32_bf16 v[72:75], v[164:167], v[216:219], v[72:75]
	v_mfma_f32_16x16x32_bf16 v[116:119], v[168:171], v[184:187], v[116:119]
	v_mfma_f32_16x16x32_bf16 v[112:115], v[176:179], v[184:187], v[112:115]
	v_mfma_f32_16x16x32_bf16 v[100:103], v[168:171], v[192:195], v[100:103]
	v_mfma_f32_16x16x32_bf16 v[96:99], v[176:179], v[192:195], v[96:99]
	v_mfma_f32_16x16x32_bf16 v[84:87], v[168:171], v[200:203], v[84:87]
	v_mfma_f32_16x16x32_bf16 v[80:83], v[176:179], v[200:203], v[80:83]
	v_mfma_f32_16x16x32_bf16 v[68:71], v[168:171], v[212:215], v[68:71]
	v_mfma_f32_16x16x32_bf16 v[64:67], v[176:179], v[212:215], v[64:67]
	v_mfma_f32_16x16x32_bf16 v[116:119], v[172:175], v[188:191], v[116:119]
	v_mfma_f32_16x16x32_bf16 v[112:115], v[180:183], v[188:191], v[112:115]
	v_mfma_f32_16x16x32_bf16 v[100:103], v[172:175], v[196:199], v[100:103]
	v_mfma_f32_16x16x32_bf16 v[96:99], v[180:183], v[196:199], v[96:99]
	v_mfma_f32_16x16x32_bf16 v[84:87], v[172:175], v[208:211], v[84:87]
	v_mfma_f32_16x16x32_bf16 v[80:83], v[180:183], v[208:211], v[80:83]
	v_mfma_f32_16x16x32_bf16 v[68:71], v[172:175], v[216:219], v[68:71]
	v_mfma_f32_16x16x32_bf16 v[64:67], v[180:183], v[216:219], v[64:67]
	s_barrier
	s_add_i32 s54, s45, s38
	s_mov_b32 m0, s54
	ds_read_b128 v[184:187], v153 offset:16384
	ds_read_b128 v[188:191], v153 offset:17408
	ds_read_b128 v[192:195], v153 offset:18432
	ds_read_b128 v[196:199], v153 offset:19456
	ds_read_b128 v[200:203], v153 offset:20480
	ds_read_b128 v[208:211], v153 offset:21504
	ds_read_b128 v[212:215], v153 offset:22528
	ds_read_b128 v[216:219], v153 offset:23552
	global_load_lds_dwordx4 v130, s[26:27]
	s_add_i32 m0, s54, 0x2000
	s_add_u32 s54, s26, 0x40000
	s_mov_b64 s[98:99], s[26:27]
	s_addc_u32 s55, s27, 0
	s_add_i32 s56, s46, s38
	global_load_lds_dwordx4 v134, s[26:27]
	s_mov_b32 m0, s56
	s_mov_b64 s[100:101], s[28:29]
	global_load_lds_dwordx4 v130, s[54:55]
	s_add_i32 m0, s56, 0x2000
	s_nop 0
	global_load_lds_dwordx4 v134, s[54:55]
	s_waitcnt vmcnt(6)
	s_waitcnt lgkmcnt(0)
	s_barrier
	s_waitcnt lgkmcnt(0)
	v_mfma_f32_16x16x32_bf16 v[60:63], v[144:147], v[184:187], v[60:63]
	v_mfma_f32_16x16x32_bf16 v[56:59], v[160:163], v[184:187], v[56:59]
	v_mfma_f32_16x16x32_bf16 v[44:47], v[144:147], v[192:195], v[44:47]
	v_mfma_f32_16x16x32_bf16 v[40:43], v[160:163], v[192:195], v[40:43]
	v_mfma_f32_16x16x32_bf16 v[28:31], v[144:147], v[200:203], v[28:31]
	v_mfma_f32_16x16x32_bf16 v[24:27], v[160:163], v[200:203], v[24:27]
	v_mfma_f32_16x16x32_bf16 v[12:15], v[144:147], v[212:215], v[12:15]
	v_mfma_f32_16x16x32_bf16 v[8:11], v[160:163], v[212:215], v[8:11]
	v_mfma_f32_16x16x32_bf16 v[60:63], v[156:159], v[188:191], v[60:63]
	v_mfma_f32_16x16x32_bf16 v[56:59], v[164:167], v[188:191], v[56:59]
	v_mfma_f32_16x16x32_bf16 v[44:47], v[156:159], v[196:199], v[44:47]
	v_mfma_f32_16x16x32_bf16 v[40:43], v[164:167], v[196:199], v[40:43]
	v_mfma_f32_16x16x32_bf16 v[28:31], v[156:159], v[208:211], v[28:31]
	v_mfma_f32_16x16x32_bf16 v[24:27], v[164:167], v[208:211], v[24:27]
	v_mfma_f32_16x16x32_bf16 v[12:15], v[156:159], v[216:219], v[12:15]
	v_mfma_f32_16x16x32_bf16 v[8:11], v[164:167], v[216:219], v[8:11]
	v_mfma_f32_16x16x32_bf16 v[52:55], v[168:171], v[184:187], v[52:55]
	v_mfma_f32_16x16x32_bf16 v[48:51], v[176:179], v[184:187], v[48:51]
	v_mfma_f32_16x16x32_bf16 v[36:39], v[168:171], v[192:195], v[36:39]
	v_mfma_f32_16x16x32_bf16 v[32:35], v[176:179], v[192:195], v[32:35]
	v_mfma_f32_16x16x32_bf16 v[20:23], v[168:171], v[200:203], v[20:23]
	v_mfma_f32_16x16x32_bf16 v[16:19], v[176:179], v[200:203], v[16:19]
	v_mfma_f32_16x16x32_bf16 v[4:7], v[168:171], v[212:215], v[4:7]
	v_mfma_f32_16x16x32_bf16 v[0:3], v[176:179], v[212:215], v[0:3]
	v_mfma_f32_16x16x32_bf16 v[52:55], v[172:175], v[188:191], v[52:55]
	v_mfma_f32_16x16x32_bf16 v[48:51], v[180:183], v[188:191], v[48:51]
	v_mfma_f32_16x16x32_bf16 v[36:39], v[172:175], v[196:199], v[36:39]
	v_mfma_f32_16x16x32_bf16 v[32:35], v[180:183], v[196:199], v[32:35]
	v_mfma_f32_16x16x32_bf16 v[20:23], v[172:175], v[208:211], v[20:23]
	v_mfma_f32_16x16x32_bf16 v[16:19], v[180:183], v[208:211], v[16:19]
	v_mfma_f32_16x16x32_bf16 v[4:7], v[172:175], v[216:219], v[4:7]
	v_mfma_f32_16x16x32_bf16 v[0:3], v[180:183], v[216:219], v[0:3]
	s_barrier
	s_mov_b32 m0, s25
	s_nop 0
	global_load_lds_dwordx4 v128, s[28:29]
	s_mov_b32 m0, s39
	s_nop 0
	global_load_lds_dwordx4 v132, s[28:29]
	s_add_i32 s54, 0, 0x18000
	s_add_i32 s55, 0, 0x1c000
	s_add_u32 s28, s28, 0x40000
	s_addc_u32 s29, s29, 0
	s_mov_b32 m0, s40
	s_nop 0
	global_load_lds_dwordx4 v128, s[28:29]
	s_mov_b32 m0, s41
	s_nop 0
	global_load_lds_dwordx4 v132, s[28:29]
	v_add_u32_e32 v155, s54, v149
	ds_read_b128 v[144:147], v155
	ds_read_b128 v[156:159], v155 offset:1024
	ds_read_b128 v[160:163], v155 offset:2048
	ds_read_b128 v[164:167], v155 offset:3072
	v_add_u32_e32 v155, s55, v149
	ds_read_b128 v[168:171], v155
	ds_read_b128 v[172:175], v155 offset:1024
	ds_read_b128 v[176:179], v155 offset:2048
	ds_read_b128 v[180:183], v155 offset:3072
	ds_read_b128 v[184:187], v153 offset:32768
	ds_read_b128 v[188:191], v153 offset:33792
	ds_read_b128 v[192:195], v153 offset:34816
	ds_read_b128 v[196:199], v153 offset:35840
	ds_read_b128 v[200:203], v153 offset:36864
	ds_read_b128 v[208:211], v153 offset:37888
	ds_read_b128 v[212:215], v153 offset:38912
	ds_read_b128 v[216:219], v153 offset:39936
	s_waitcnt vmcnt(8)
	s_waitcnt lgkmcnt(0)
	s_barrier
	s_waitcnt lgkmcnt(0)
	v_mfma_f32_16x16x32_bf16 v[124:127], v[144:147], v[184:187], v[124:127]
	v_mfma_f32_16x16x32_bf16 v[120:123], v[160:163], v[184:187], v[120:123]
	v_mfma_f32_16x16x32_bf16 v[108:111], v[144:147], v[192:195], v[108:111]
	v_mfma_f32_16x16x32_bf16 v[104:107], v[160:163], v[192:195], v[104:107]
	v_mfma_f32_16x16x32_bf16 v[92:95], v[144:147], v[200:203], v[92:95]
	v_mfma_f32_16x16x32_bf16 v[88:91], v[160:163], v[200:203], v[88:91]
	v_mfma_f32_16x16x32_bf16 v[76:79], v[144:147], v[212:215], v[76:79]
	v_mfma_f32_16x16x32_bf16 v[72:75], v[160:163], v[212:215], v[72:75]
	v_mfma_f32_16x16x32_bf16 v[124:127], v[156:159], v[188:191], v[124:127]
	v_mfma_f32_16x16x32_bf16 v[120:123], v[164:167], v[188:191], v[120:123]
	v_mfma_f32_16x16x32_bf16 v[108:111], v[156:159], v[196:199], v[108:111]
	v_mfma_f32_16x16x32_bf16 v[104:107], v[164:167], v[196:199], v[104:107]
	v_mfma_f32_16x16x32_bf16 v[92:95], v[156:159], v[208:211], v[92:95]
	v_mfma_f32_16x16x32_bf16 v[88:91], v[164:167], v[208:211], v[88:91]
	v_mfma_f32_16x16x32_bf16 v[76:79], v[156:159], v[216:219], v[76:79]
	v_mfma_f32_16x16x32_bf16 v[72:75], v[164:167], v[216:219], v[72:75]
	v_mfma_f32_16x16x32_bf16 v[116:119], v[168:171], v[184:187], v[116:119]
	v_mfma_f32_16x16x32_bf16 v[112:115], v[176:179], v[184:187], v[112:115]
	v_mfma_f32_16x16x32_bf16 v[100:103], v[168:171], v[192:195], v[100:103]
	v_mfma_f32_16x16x32_bf16 v[96:99], v[176:179], v[192:195], v[96:99]
	v_mfma_f32_16x16x32_bf16 v[84:87], v[168:171], v[200:203], v[84:87]
	v_mfma_f32_16x16x32_bf16 v[80:83], v[176:179], v[200:203], v[80:83]
	v_mfma_f32_16x16x32_bf16 v[68:71], v[168:171], v[212:215], v[68:71]
	v_mfma_f32_16x16x32_bf16 v[64:67], v[176:179], v[212:215], v[64:67]
	v_mfma_f32_16x16x32_bf16 v[116:119], v[172:175], v[188:191], v[116:119]
	v_mfma_f32_16x16x32_bf16 v[112:115], v[180:183], v[188:191], v[112:115]
	v_mfma_f32_16x16x32_bf16 v[100:103], v[172:175], v[196:199], v[100:103]
	v_mfma_f32_16x16x32_bf16 v[96:99], v[180:183], v[196:199], v[96:99]
	v_mfma_f32_16x16x32_bf16 v[84:87], v[172:175], v[208:211], v[84:87]
	v_mfma_f32_16x16x32_bf16 v[80:83], v[180:183], v[208:211], v[80:83]
	v_mfma_f32_16x16x32_bf16 v[68:71], v[172:175], v[216:219], v[68:71]
	v_mfma_f32_16x16x32_bf16 v[64:67], v[180:183], v[216:219], v[64:67]
	s_barrier
	s_add_i32 s28, s54, s38
	s_mov_b32 m0, s28
	ds_read_b128 v[184:187], v153 offset:49152
	ds_read_b128 v[188:191], v153 offset:50176
	ds_read_b128 v[192:195], v153 offset:51200
	ds_read_b128 v[196:199], v153 offset:52224
	ds_read_b128 v[200:203], v153 offset:53248
	ds_read_b128 v[208:211], v153 offset:54272
	ds_read_b128 v[212:215], v153 offset:55296
	ds_read_b128 v[216:219], v153 offset:56320
	global_load_lds_dwordx4 v205, s[26:27]
	s_add_i32 m0, s28, 0x2000
	s_add_u32 s26, s26, 0x40080
	s_addc_u32 s27, s27, 0
	s_add_i32 s28, s55, s38
	global_load_lds_dwordx4 v221, s[98:99]
	s_mov_b32 m0, s28
	s_nop 0
	global_load_lds_dwordx4 v130, s[26:27]
	s_add_i32 m0, s28, 0x2000
	s_nop 0
	global_load_lds_dwordx4 v134, s[26:27]
	s_cmp_lg_u32 s53, 12
	s_cbranch_scc1 .Lbal_last_16
	s_mov_b32 m0, s43
	s_nop 0
	global_load_lds_dwordx4 v204, s[100:101]
	s_mov_b32 m0, s44
	s_nop 0
	global_load_lds_dwordx4 v220, s[100:101]

.Lbal_first_15:
	s_add_u32 s26, s24, 0xfffe0080
	s_addc_u32 s27, s25, -1
	s_cmp_eq_u32 s50, 4
	s_cselect_b32 s29, s17, s27
	s_cselect_b32 s28, s46, s26
	s_cselect_b32 s27, s15, s49
	s_cselect_b32 s26, s47, s48
	s_add_i32 m0, s23, 0xc000
	s_nop 0
	global_load_lds_dwordx4 v138, s[24:25]
	s_add_i32 m0, s23, 0xe000
	s_nop 0
	global_load_lds_dwordx4 v136, s[24:25]
	ds_read_b128 v[144:147], v151
	ds_read_b128 v[154:157], v151 offset:1024
	ds_read_b128 v[158:161], v151 offset:2048
	ds_read_b128 v[162:165], v151 offset:3072
	ds_read_b128 v[166:169], v152
	ds_read_b128 v[170:173], v152 offset:1024
	ds_read_b128 v[174:177], v152 offset:2048
	ds_read_b128 v[178:181], v152 offset:3072
	ds_read_b128 v[182:185], v153
	ds_read_b128 v[186:189], v153 offset:1024
	ds_read_b128 v[190:193], v153 offset:2048
	ds_read_b128 v[194:197], v153 offset:3072
	ds_read_b128 v[198:201], v153 offset:4096
	ds_read_b128 v[202:205], v153 offset:5120
	ds_read_b128 v[208:211], v153 offset:6144
	ds_read_b128 v[212:215], v153 offset:7168
	s_waitcnt vmcnt(8)
	s_waitcnt lgkmcnt(0)
	s_barrier
	s_waitcnt lgkmcnt(0)
	v_mfma_f32_16x16x32_bf16 v[124:127], v[144:147], v[182:185], v[124:127]
	v_mfma_f32_16x16x32_bf16 v[120:123], v[158:161], v[182:185], v[120:123]
	v_mfma_f32_16x16x32_bf16 v[108:111], v[144:147], v[190:193], v[108:111]
	v_mfma_f32_16x16x32_bf16 v[104:107], v[158:161], v[190:193], v[104:107]
	v_mfma_f32_16x16x32_bf16 v[92:95], v[144:147], v[198:201], v[92:95]
	v_mfma_f32_16x16x32_bf16 v[88:91], v[158:161], v[198:201], v[88:91]
	v_mfma_f32_16x16x32_bf16 v[76:79], v[144:147], v[208:211], v[76:79]
	v_mfma_f32_16x16x32_bf16 v[72:75], v[158:161], v[208:211], v[72:75]
	v_mfma_f32_16x16x32_bf16 v[124:127], v[154:157], v[186:189], v[124:127]
	v_mfma_f32_16x16x32_bf16 v[120:123], v[162:165], v[186:189], v[120:123]
	v_mfma_f32_16x16x32_bf16 v[108:111], v[154:157], v[194:197], v[108:111]
	v_mfma_f32_16x16x32_bf16 v[104:107], v[162:165], v[194:197], v[104:107]
	v_mfma_f32_16x16x32_bf16 v[92:95], v[154:157], v[202:205], v[92:95]
	v_mfma_f32_16x16x32_bf16 v[88:91], v[162:165], v[202:205], v[88:91]
	v_mfma_f32_16x16x32_bf16 v[76:79], v[154:157], v[212:215], v[76:79]
	v_mfma_f32_16x16x32_bf16 v[72:75], v[162:165], v[212:215], v[72:75]
	v_mfma_f32_16x16x32_bf16 v[116:119], v[166:169], v[182:185], v[116:119]
	v_mfma_f32_16x16x32_bf16 v[112:115], v[174:177], v[182:185], v[112:115]
	v_mfma_f32_16x16x32_bf16 v[100:103], v[166:169], v[190:193], v[100:103]
	v_mfma_f32_16x16x32_bf16 v[96:99], v[174:177], v[190:193], v[96:99]
	v_mfma_f32_16x16x32_bf16 v[84:87], v[166:169], v[198:201], v[84:87]
	v_mfma_f32_16x16x32_bf16 v[80:83], v[174:177], v[198:201], v[80:83]
	v_mfma_f32_16x16x32_bf16 v[68:71], v[166:169], v[208:211], v[68:71]
	v_mfma_f32_16x16x32_bf16 v[64:67], v[174:177], v[208:211], v[64:67]
	v_mfma_f32_16x16x32_bf16 v[116:119], v[170:173], v[186:189], v[116:119]
	v_mfma_f32_16x16x32_bf16 v[112:115], v[178:181], v[186:189], v[112:115]
	v_mfma_f32_16x16x32_bf16 v[100:103], v[170:173], v[194:197], v[100:103]
	v_mfma_f32_16x16x32_bf16 v[96:99], v[178:181], v[194:197], v[96:99]
	v_mfma_f32_16x16x32_bf16 v[84:87], v[170:173], v[202:205], v[84:87]
	v_mfma_f32_16x16x32_bf16 v[80:83], v[178:181], v[202:205], v[80:83]
	v_mfma_f32_16x16x32_bf16 v[68:71], v[170:173], v[212:215], v[68:71]
	v_mfma_f32_16x16x32_bf16 v[64:67], v[178:181], v[212:215], v[64:67]
	s_barrier
	s_add_i32 s51, s43, s36
	s_mov_b32 m0, s51
	ds_read_b128 v[182:185], v153 offset:16384
	ds_read_b128 v[186:189], v153 offset:17408
	ds_read_b128 v[190:193], v153 offset:18432
	ds_read_b128 v[194:197], v153 offset:19456
	ds_read_b128 v[198:201], v153 offset:20480
	ds_read_b128 v[202:205], v153 offset:21504
	ds_read_b128 v[208:211], v153 offset:22528
	ds_read_b128 v[212:215], v153 offset:23552
	global_load_lds_dwordx4 v130, s[26:27]
	s_add_i32 m0, s51, 0x2000
	s_add_u32 s52, s26, 0x20000
	s_mov_b64 s[98:99], s[26:27]
	s_addc_u32 s53, s27, 0
	s_add_i32 s51, s44, s36
	global_load_lds_dwordx4 v134, s[26:27]
	s_mov_b32 m0, s51
	s_mov_b64 s[100:101], s[28:29]
	global_load_lds_dwordx4 v130, s[52:53]
	s_add_i32 m0, s51, 0x2000
	s_nop 0
	global_load_lds_dwordx4 v134, s[52:53]
	s_waitcnt vmcnt(6)
	s_waitcnt lgkmcnt(0)
	s_barrier
	s_waitcnt lgkmcnt(0)
	v_mfma_f32_16x16x32_bf16 v[60:63], v[144:147], v[182:185], v[60:63]
	v_mfma_f32_16x16x32_bf16 v[56:59], v[158:161], v[182:185], v[56:59]
	v_mfma_f32_16x16x32_bf16 v[44:47], v[144:147], v[190:193], v[44:47]
	v_mfma_f32_16x16x32_bf16 v[40:43], v[158:161], v[190:193], v[40:43]
	v_mfma_f32_16x16x32_bf16 v[28:31], v[144:147], v[198:201], v[28:31]
	v_mfma_f32_16x16x32_bf16 v[24:27], v[158:161], v[198:201], v[24:27]
	v_mfma_f32_16x16x32_bf16 v[12:15], v[144:147], v[208:211], v[12:15]
	v_mfma_f32_16x16x32_bf16 v[8:11], v[158:161], v[208:211], v[8:11]
	v_mfma_f32_16x16x32_bf16 v[60:63], v[154:157], v[186:189], v[60:63]
	v_mfma_f32_16x16x32_bf16 v[56:59], v[162:165], v[186:189], v[56:59]
	v_mfma_f32_16x16x32_bf16 v[44:47], v[154:157], v[194:197], v[44:47]
	v_mfma_f32_16x16x32_bf16 v[40:43], v[162:165], v[194:197], v[40:43]
	v_mfma_f32_16x16x32_bf16 v[28:31], v[154:157], v[202:205], v[28:31]
	v_mfma_f32_16x16x32_bf16 v[24:27], v[162:165], v[202:205], v[24:27]
	v_mfma_f32_16x16x32_bf16 v[12:15], v[154:157], v[212:215], v[12:15]
	v_mfma_f32_16x16x32_bf16 v[8:11], v[162:165], v[212:215], v[8:11]
	v_mfma_f32_16x16x32_bf16 v[52:55], v[166:169], v[182:185], v[52:55]
	v_mfma_f32_16x16x32_bf16 v[48:51], v[174:177], v[182:185], v[48:51]
	v_mfma_f32_16x16x32_bf16 v[36:39], v[166:169], v[190:193], v[36:39]
	v_mfma_f32_16x16x32_bf16 v[32:35], v[174:177], v[190:193], v[32:35]
	v_mfma_f32_16x16x32_bf16 v[20:23], v[166:169], v[198:201], v[20:23]
	v_mfma_f32_16x16x32_bf16 v[16:19], v[174:177], v[198:201], v[16:19]
	v_mfma_f32_16x16x32_bf16 v[4:7], v[166:169], v[208:211], v[4:7]
	v_mfma_f32_16x16x32_bf16 v[0:3], v[174:177], v[208:211], v[0:3]
	v_mfma_f32_16x16x32_bf16 v[52:55], v[170:173], v[186:189], v[52:55]
	v_mfma_f32_16x16x32_bf16 v[48:51], v[178:181], v[186:189], v[48:51]
	v_mfma_f32_16x16x32_bf16 v[36:39], v[170:173], v[194:197], v[36:39]
	v_mfma_f32_16x16x32_bf16 v[32:35], v[178:181], v[194:197], v[32:35]
	v_mfma_f32_16x16x32_bf16 v[20:23], v[170:173], v[202:205], v[20:23]
	v_mfma_f32_16x16x32_bf16 v[16:19], v[178:181], v[202:205], v[16:19]
	v_mfma_f32_16x16x32_bf16 v[4:7], v[170:173], v[212:215], v[4:7]
	v_mfma_f32_16x16x32_bf16 v[0:3], v[178:181], v[212:215], v[0:3]
	s_barrier
	s_mov_b32 m0, s23
	s_nop 0
	global_load_lds_dwordx4 v128, s[28:29]
	s_mov_b32 m0, s37
	s_nop 0
	global_load_lds_dwordx4 v132, s[28:29]
	s_add_i32 s51, 0, 0x18000
	s_add_i32 s52, 0, 0x1c000
	s_add_u32 s28, s28, 0x20000
	s_addc_u32 s29, s29, 0
	s_mov_b32 m0, s38
	s_nop 0
	global_load_lds_dwordx4 v128, s[28:29]
	s_mov_b32 m0, s39
	s_nop 0
	global_load_lds_dwordx4 v132, s[28:29]
	v_add_u32_e32 v162, s51, v149
	v_add_u32_e32 v178, s52, v149
	ds_read_b128 v[144:147], v162
	ds_read_b128 v[154:157], v162 offset:1024
	ds_read_b128 v[158:161], v162 offset:2048
	ds_read_b128 v[162:165], v162 offset:3072
	ds_read_b128 v[166:169], v178
	ds_read_b128 v[170:173], v178 offset:1024
	ds_read_b128 v[174:177], v178 offset:2048
	ds_read_b128 v[178:181], v178 offset:3072
	ds_read_b128 v[182:185], v153 offset:32768
	ds_read_b128 v[186:189], v153 offset:33792
	ds_read_b128 v[190:193], v153 offset:34816
	ds_read_b128 v[194:197], v153 offset:35840
	ds_read_b128 v[198:201], v153 offset:36864
	ds_read_b128 v[202:205], v153 offset:37888
	ds_read_b128 v[208:211], v153 offset:38912
	ds_read_b128 v[212:215], v153 offset:39936
	s_waitcnt vmcnt(8)
	s_waitcnt lgkmcnt(0)
	s_barrier
	s_waitcnt lgkmcnt(0)
	v_mfma_f32_16x16x32_bf16 v[124:127], v[144:147], v[182:185], v[124:127]
	v_mfma_f32_16x16x32_bf16 v[120:123], v[158:161], v[182:185], v[120:123]
	v_mfma_f32_16x16x32_bf16 v[108:111], v[144:147], v[190:193], v[108:111]
	v_mfma_f32_16x16x32_bf16 v[104:107], v[158:161], v[190:193], v[104:107]
	v_mfma_f32_16x16x32_bf16 v[92:95], v[144:147], v[198:201], v[92:95]
	v_mfma_f32_16x16x32_bf16 v[88:91], v[158:161], v[198:201], v[88:91]
	v_mfma_f32_16x16x32_bf16 v[76:79], v[144:147], v[208:211], v[76:79]
	v_mfma_f32_16x16x32_bf16 v[72:75], v[158:161], v[208:211], v[72:75]
	v_mfma_f32_16x16x32_bf16 v[124:127], v[154:157], v[186:189], v[124:127]
	v_mfma_f32_16x16x32_bf16 v[120:123], v[162:165], v[186:189], v[120:123]
	v_mfma_f32_16x16x32_bf16 v[108:111], v[154:157], v[194:197], v[108:111]
	v_mfma_f32_16x16x32_bf16 v[104:107], v[162:165], v[194:197], v[104:107]
	v_mfma_f32_16x16x32_bf16 v[92:95], v[154:157], v[202:205], v[92:95]
	v_mfma_f32_16x16x32_bf16 v[88:91], v[162:165], v[202:205], v[88:91]
	v_mfma_f32_16x16x32_bf16 v[76:79], v[154:157], v[212:215], v[76:79]
	v_mfma_f32_16x16x32_bf16 v[72:75], v[162:165], v[212:215], v[72:75]
	v_mfma_f32_16x16x32_bf16 v[116:119], v[166:169], v[182:185], v[116:119]
	v_mfma_f32_16x16x32_bf16 v[112:115], v[174:177], v[182:185], v[112:115]
	v_mfma_f32_16x16x32_bf16 v[100:103], v[166:169], v[190:193], v[100:103]
	v_mfma_f32_16x16x32_bf16 v[96:99], v[174:177], v[190:193], v[96:99]
	v_mfma_f32_16x16x32_bf16 v[84:87], v[166:169], v[198:201], v[84:87]
	v_mfma_f32_16x16x32_bf16 v[80:83], v[174:177], v[198:201], v[80:83]
	v_mfma_f32_16x16x32_bf16 v[68:71], v[166:169], v[208:211], v[68:71]
	v_mfma_f32_16x16x32_bf16 v[64:67], v[174:177], v[208:211], v[64:67]
	v_mfma_f32_16x16x32_bf16 v[116:119], v[170:173], v[186:189], v[116:119]
	v_mfma_f32_16x16x32_bf16 v[112:115], v[178:181], v[186:189], v[112:115]
	v_mfma_f32_16x16x32_bf16 v[100:103], v[170:173], v[194:197], v[100:103]
	v_mfma_f32_16x16x32_bf16 v[96:99], v[178:181], v[194:197], v[96:99]
	v_mfma_f32_16x16x32_bf16 v[84:87], v[170:173], v[202:205], v[84:87]
	v_mfma_f32_16x16x32_bf16 v[80:83], v[178:181], v[202:205], v[80:83]
	v_mfma_f32_16x16x32_bf16 v[68:71], v[170:173], v[212:215], v[68:71]
	v_mfma_f32_16x16x32_bf16 v[64:67], v[178:181], v[212:215], v[64:67]
	s_barrier
	s_add_i32 s28, s51, s36
	s_mov_b32 m0, s28
	ds_read_b128 v[182:185], v153 offset:49152
	ds_read_b128 v[186:189], v153 offset:50176
	ds_read_b128 v[190:193], v153 offset:51200
	ds_read_b128 v[194:197], v153 offset:52224
	ds_read_b128 v[198:201], v153 offset:53248
	ds_read_b128 v[202:205], v153 offset:54272
	ds_read_b128 v[208:211], v153 offset:55296
	ds_read_b128 v[212:215], v153 offset:56320
	global_load_lds_dwordx4 v217, s[26:27]
	s_add_i32 m0, s28, 0x2000
	s_add_u32 s26, s26, 0x20080
	s_addc_u32 s27, s27, 0
	s_add_i32 s28, s52, s36
	global_load_lds_dwordx4 v219, s[98:99]
	s_mov_b32 m0, s28
	s_nop 0
	global_load_lds_dwordx4 v130, s[26:27]
	s_add_i32 m0, s28, 0x2000
	s_nop 0
	global_load_lds_dwordx4 v134, s[26:27]
	s_cmp_lg_u32 s50, 4
	s_cbranch_scc1 .Lbal_last_15
	s_mov_b32 m0, s41
	s_nop 0
	global_load_lds_dwordx4 v216, s[100:101]
	s_mov_b32 m0, s42
	s_nop 0
	global_load_lds_dwordx4 v218, s[100:101]

.Lbal_first_13:
	s_add_u32 s26, s24, 0xfffc0080
	s_addc_u32 s27, s25, -1
	s_cmp_eq_u32 s53, 12
	s_cselect_b32 s29, s19, s27
	s_cselect_b32 s28, s49, s26
	s_cselect_b32 s27, s17, s52
	s_cselect_b32 s26, s50, s51
	s_add_i32 m0, s39, 0xc000
	s_nop 0
	global_load_lds_dwordx4 v138, s[24:25]
	s_add_i32 m0, s39, 0xe000
	s_nop 0
	global_load_lds_dwordx4 v136, s[24:25]
	ds_read_b128 v[144:147], v151
	ds_read_b128 v[156:159], v151 offset:1024
	ds_read_b128 v[160:163], v151 offset:2048
	ds_read_b128 v[164:167], v151 offset:3072
	ds_read_b128 v[168:171], v152
	ds_read_b128 v[172:175], v152 offset:1024
	ds_read_b128 v[176:179], v152 offset:2048
	ds_read_b128 v[180:183], v152 offset:3072
	ds_read_b128 v[184:187], v153
	ds_read_b128 v[188:191], v153 offset:1024
	ds_read_b128 v[192:195], v153 offset:2048
	ds_read_b128 v[196:199], v153 offset:3072
	ds_read_b128 v[200:203], v153 offset:4096
	ds_read_b128 v[208:211], v153 offset:5120
	ds_read_b128 v[212:215], v153 offset:6144
	ds_read_b128 v[216:219], v153 offset:7168
	s_waitcnt vmcnt(8)
	s_waitcnt lgkmcnt(0)
	s_barrier
	s_waitcnt lgkmcnt(0)
	v_mfma_f32_16x16x32_bf16 v[124:127], v[144:147], v[184:187], v[124:127]
	v_mfma_f32_16x16x32_bf16 v[120:123], v[160:163], v[184:187], v[120:123]
	v_mfma_f32_16x16x32_bf16 v[108:111], v[144:147], v[192:195], v[108:111]
	v_mfma_f32_16x16x32_bf16 v[104:107], v[160:163], v[192:195], v[104:107]
	v_mfma_f32_16x16x32_bf16 v[92:95], v[144:147], v[200:203], v[92:95]
	v_mfma_f32_16x16x32_bf16 v[88:91], v[160:163], v[200:203], v[88:91]
	v_mfma_f32_16x16x32_bf16 v[76:79], v[144:147], v[212:215], v[76:79]
	v_mfma_f32_16x16x32_bf16 v[72:75], v[160:163], v[212:215], v[72:75]
	v_mfma_f32_16x16x32_bf16 v[124:127], v[156:159], v[188:191], v[124:127]
	v_mfma_f32_16x16x32_bf16 v[120:123], v[164:167], v[188:191], v[120:123]
	v_mfma_f32_16x16x32_bf16 v[108:111], v[156:159], v[196:199], v[108:111]
	v_mfma_f32_16x16x32_bf16 v[104:107], v[164:167], v[196:199], v[104:107]
	v_mfma_f32_16x16x32_bf16 v[92:95], v[156:159], v[208:211], v[92:95]
	v_mfma_f32_16x16x32_bf16 v[88:91], v[164:167], v[208:211], v[88:91]
	v_mfma_f32_16x16x32_bf16 v[76:79], v[156:159], v[216:219], v[76:79]
	v_mfma_f32_16x16x32_bf16 v[72:75], v[164:167], v[216:219], v[72:75]
	v_mfma_f32_16x16x32_bf16 v[116:119], v[168:171], v[184:187], v[116:119]
	v_mfma_f32_16x16x32_bf16 v[112:115], v[176:179], v[184:187], v[112:115]
	v_mfma_f32_16x16x32_bf16 v[100:103], v[168:171], v[192:195], v[100:103]
	v_mfma_f32_16x16x32_bf16 v[96:99], v[176:179], v[192:195], v[96:99]
	v_mfma_f32_16x16x32_bf16 v[84:87], v[168:171], v[200:203], v[84:87]
	v_mfma_f32_16x16x32_bf16 v[80:83], v[176:179], v[200:203], v[80:83]
	v_mfma_f32_16x16x32_bf16 v[68:71], v[168:171], v[212:215], v[68:71]
	v_mfma_f32_16x16x32_bf16 v[64:67], v[176:179], v[212:215], v[64:67]
	v_mfma_f32_16x16x32_bf16 v[116:119], v[172:175], v[188:191], v[116:119]
	v_mfma_f32_16x16x32_bf16 v[112:115], v[180:183], v[188:191], v[112:115]
	v_mfma_f32_16x16x32_bf16 v[100:103], v[172:175], v[196:199], v[100:103]
	v_mfma_f32_16x16x32_bf16 v[96:99], v[180:183], v[196:199], v[96:99]
	v_mfma_f32_16x16x32_bf16 v[84:87], v[172:175], v[208:211], v[84:87]
	v_mfma_f32_16x16x32_bf16 v[80:83], v[180:183], v[208:211], v[80:83]
	v_mfma_f32_16x16x32_bf16 v[68:71], v[172:175], v[216:219], v[68:71]
	v_mfma_f32_16x16x32_bf16 v[64:67], v[180:183], v[216:219], v[64:67]
	s_barrier
	s_add_i32 s54, s46, s38
	s_mov_b32 m0, s54
	ds_read_b128 v[184:187], v153 offset:16384
	ds_read_b128 v[188:191], v153 offset:17408
	ds_read_b128 v[192:195], v153 offset:18432
	ds_read_b128 v[196:199], v153 offset:19456
	ds_read_b128 v[200:203], v153 offset:20480
	ds_read_b128 v[208:211], v153 offset:21504
	ds_read_b128 v[212:215], v153 offset:22528
	ds_read_b128 v[216:219], v153 offset:23552
	global_load_lds_dwordx4 v130, s[26:27]
	s_add_i32 m0, s54, 0x2000
	s_add_u32 s54, s26, 0x40000
	s_mov_b64 s[98:99], s[26:27]
	s_addc_u32 s55, s27, 0
	s_add_i32 s56, s47, s38
	global_load_lds_dwordx4 v134, s[26:27]
	s_mov_b32 m0, s56
	s_mov_b64 s[100:101], s[28:29]
	global_load_lds_dwordx4 v130, s[54:55]
	s_add_i32 m0, s56, 0x2000
	s_nop 0
	global_load_lds_dwordx4 v134, s[54:55]
	s_waitcnt vmcnt(6)
	s_waitcnt lgkmcnt(0)
	s_barrier
	s_waitcnt lgkmcnt(0)
	v_mfma_f32_16x16x32_bf16 v[60:63], v[144:147], v[184:187], v[60:63]
	v_mfma_f32_16x16x32_bf16 v[56:59], v[160:163], v[184:187], v[56:59]
	v_mfma_f32_16x16x32_bf16 v[44:47], v[144:147], v[192:195], v[44:47]
	v_mfma_f32_16x16x32_bf16 v[40:43], v[160:163], v[192:195], v[40:43]
	v_mfma_f32_16x16x32_bf16 v[28:31], v[144:147], v[200:203], v[28:31]
	v_mfma_f32_16x16x32_bf16 v[24:27], v[160:163], v[200:203], v[24:27]
	v_mfma_f32_16x16x32_bf16 v[12:15], v[144:147], v[212:215], v[12:15]
	v_mfma_f32_16x16x32_bf16 v[8:11], v[160:163], v[212:215], v[8:11]
	v_mfma_f32_16x16x32_bf16 v[60:63], v[156:159], v[188:191], v[60:63]
	v_mfma_f32_16x16x32_bf16 v[56:59], v[164:167], v[188:191], v[56:59]
	v_mfma_f32_16x16x32_bf16 v[44:47], v[156:159], v[196:199], v[44:47]
	v_mfma_f32_16x16x32_bf16 v[40:43], v[164:167], v[196:199], v[40:43]
	v_mfma_f32_16x16x32_bf16 v[28:31], v[156:159], v[208:211], v[28:31]
	v_mfma_f32_16x16x32_bf16 v[24:27], v[164:167], v[208:211], v[24:27]
	v_mfma_f32_16x16x32_bf16 v[12:15], v[156:159], v[216:219], v[12:15]
	v_mfma_f32_16x16x32_bf16 v[8:11], v[164:167], v[216:219], v[8:11]
	v_mfma_f32_16x16x32_bf16 v[52:55], v[168:171], v[184:187], v[52:55]
	v_mfma_f32_16x16x32_bf16 v[48:51], v[176:179], v[184:187], v[48:51]
	v_mfma_f32_16x16x32_bf16 v[36:39], v[168:171], v[192:195], v[36:39]
	v_mfma_f32_16x16x32_bf16 v[32:35], v[176:179], v[192:195], v[32:35]
	v_mfma_f32_16x16x32_bf16 v[20:23], v[168:171], v[200:203], v[20:23]
	v_mfma_f32_16x16x32_bf16 v[16:19], v[176:179], v[200:203], v[16:19]
	v_mfma_f32_16x16x32_bf16 v[4:7], v[168:171], v[212:215], v[4:7]
	v_mfma_f32_16x16x32_bf16 v[0:3], v[176:179], v[212:215], v[0:3]
	v_mfma_f32_16x16x32_bf16 v[52:55], v[172:175], v[188:191], v[52:55]
	v_mfma_f32_16x16x32_bf16 v[48:51], v[180:183], v[188:191], v[48:51]
	v_mfma_f32_16x16x32_bf16 v[36:39], v[172:175], v[196:199], v[36:39]
	v_mfma_f32_16x16x32_bf16 v[32:35], v[180:183], v[196:199], v[32:35]
	v_mfma_f32_16x16x32_bf16 v[20:23], v[172:175], v[208:211], v[20:23]
	v_mfma_f32_16x16x32_bf16 v[16:19], v[180:183], v[208:211], v[16:19]
	v_mfma_f32_16x16x32_bf16 v[4:7], v[172:175], v[216:219], v[4:7]
	v_mfma_f32_16x16x32_bf16 v[0:3], v[180:183], v[216:219], v[0:3]
	s_barrier
	s_mov_b32 m0, s39
	s_nop 0
	global_load_lds_dwordx4 v128, s[28:29]
	s_mov_b32 m0, s40
	s_nop 0
	global_load_lds_dwordx4 v132, s[28:29]
	s_add_i32 s54, 0, 0x18000
	s_add_i32 s55, 0, 0x1c000
	s_add_u32 s28, s28, 0x40000
	s_addc_u32 s29, s29, 0
	s_mov_b32 m0, s41
	s_nop 0
	global_load_lds_dwordx4 v128, s[28:29]
	s_mov_b32 m0, s42
	s_nop 0
	global_load_lds_dwordx4 v132, s[28:29]
	v_add_u32_e32 v155, s54, v149
	ds_read_b128 v[144:147], v155
	ds_read_b128 v[156:159], v155 offset:1024
	ds_read_b128 v[160:163], v155 offset:2048
	ds_read_b128 v[164:167], v155 offset:3072
	v_add_u32_e32 v155, s55, v149
	ds_read_b128 v[168:171], v155
	ds_read_b128 v[172:175], v155 offset:1024
	ds_read_b128 v[176:179], v155 offset:2048
	ds_read_b128 v[180:183], v155 offset:3072
	ds_read_b128 v[184:187], v153 offset:32768
	ds_read_b128 v[188:191], v153 offset:33792
	ds_read_b128 v[192:195], v153 offset:34816
	ds_read_b128 v[196:199], v153 offset:35840
	ds_read_b128 v[200:203], v153 offset:36864
	ds_read_b128 v[208:211], v153 offset:37888
	ds_read_b128 v[212:215], v153 offset:38912
	ds_read_b128 v[216:219], v153 offset:39936
	s_waitcnt vmcnt(8)
	s_waitcnt lgkmcnt(0)
	s_barrier
	s_waitcnt lgkmcnt(0)
	v_mfma_f32_16x16x32_bf16 v[124:127], v[144:147], v[184:187], v[124:127]
	v_mfma_f32_16x16x32_bf16 v[120:123], v[160:163], v[184:187], v[120:123]
	v_mfma_f32_16x16x32_bf16 v[108:111], v[144:147], v[192:195], v[108:111]
	v_mfma_f32_16x16x32_bf16 v[104:107], v[160:163], v[192:195], v[104:107]
	v_mfma_f32_16x16x32_bf16 v[92:95], v[144:147], v[200:203], v[92:95]
	v_mfma_f32_16x16x32_bf16 v[88:91], v[160:163], v[200:203], v[88:91]
	v_mfma_f32_16x16x32_bf16 v[76:79], v[144:147], v[212:215], v[76:79]
	v_mfma_f32_16x16x32_bf16 v[72:75], v[160:163], v[212:215], v[72:75]
	v_mfma_f32_16x16x32_bf16 v[124:127], v[156:159], v[188:191], v[124:127]
	v_mfma_f32_16x16x32_bf16 v[120:123], v[164:167], v[188:191], v[120:123]
	v_mfma_f32_16x16x32_bf16 v[108:111], v[156:159], v[196:199], v[108:111]
	v_mfma_f32_16x16x32_bf16 v[104:107], v[164:167], v[196:199], v[104:107]
	v_mfma_f32_16x16x32_bf16 v[92:95], v[156:159], v[208:211], v[92:95]
	v_mfma_f32_16x16x32_bf16 v[88:91], v[164:167], v[208:211], v[88:91]
	v_mfma_f32_16x16x32_bf16 v[76:79], v[156:159], v[216:219], v[76:79]
	v_mfma_f32_16x16x32_bf16 v[72:75], v[164:167], v[216:219], v[72:75]
	v_mfma_f32_16x16x32_bf16 v[116:119], v[168:171], v[184:187], v[116:119]
	v_mfma_f32_16x16x32_bf16 v[112:115], v[176:179], v[184:187], v[112:115]
	v_mfma_f32_16x16x32_bf16 v[100:103], v[168:171], v[192:195], v[100:103]
	v_mfma_f32_16x16x32_bf16 v[96:99], v[176:179], v[192:195], v[96:99]
	v_mfma_f32_16x16x32_bf16 v[84:87], v[168:171], v[200:203], v[84:87]
	v_mfma_f32_16x16x32_bf16 v[80:83], v[176:179], v[200:203], v[80:83]
	v_mfma_f32_16x16x32_bf16 v[68:71], v[168:171], v[212:215], v[68:71]
	v_mfma_f32_16x16x32_bf16 v[64:67], v[176:179], v[212:215], v[64:67]
	v_mfma_f32_16x16x32_bf16 v[116:119], v[172:175], v[188:191], v[116:119]
	v_mfma_f32_16x16x32_bf16 v[112:115], v[180:183], v[188:191], v[112:115]
	v_mfma_f32_16x16x32_bf16 v[100:103], v[172:175], v[196:199], v[100:103]
	v_mfma_f32_16x16x32_bf16 v[96:99], v[180:183], v[196:199], v[96:99]
	v_mfma_f32_16x16x32_bf16 v[84:87], v[172:175], v[208:211], v[84:87]
	v_mfma_f32_16x16x32_bf16 v[80:83], v[180:183], v[208:211], v[80:83]
	v_mfma_f32_16x16x32_bf16 v[68:71], v[172:175], v[216:219], v[68:71]
	v_mfma_f32_16x16x32_bf16 v[64:67], v[180:183], v[216:219], v[64:67]
	s_barrier
	s_add_i32 s28, s54, s38
	s_mov_b32 m0, s28
	ds_read_b128 v[184:187], v153 offset:49152
	ds_read_b128 v[188:191], v153 offset:50176
	ds_read_b128 v[192:195], v153 offset:51200
	ds_read_b128 v[196:199], v153 offset:52224
	ds_read_b128 v[200:203], v153 offset:53248
	ds_read_b128 v[208:211], v153 offset:54272
	ds_read_b128 v[212:215], v153 offset:55296
	ds_read_b128 v[216:219], v153 offset:56320
	global_load_lds_dwordx4 v205, s[26:27]
	s_add_i32 m0, s28, 0x2000
	s_add_u32 s26, s26, 0x40080
	s_addc_u32 s27, s27, 0
	s_add_i32 s28, s55, s38
	global_load_lds_dwordx4 v221, s[98:99]
	s_mov_b32 m0, s28
	s_nop 0
	global_load_lds_dwordx4 v130, s[26:27]
	s_add_i32 m0, s28, 0x2000
	s_nop 0
	global_load_lds_dwordx4 v134, s[26:27]
	s_cmp_lg_u32 s53, 12
	s_cbranch_scc1 .Lbal_last_13
	s_mov_b32 m0, s44
	s_nop 0
	global_load_lds_dwordx4 v204, s[100:101]
	s_mov_b32 m0, s45
	s_nop 0
	global_load_lds_dwordx4 v220, s[100:101]

.Lbal_first_11:
	s_add_u32 s38, s36, 0xfffc0080
	s_addc_u32 s39, s37, -1
	s_cmp_eq_u32 s61, 12
	s_cselect_b32 s41, s3, s39
	s_cselect_b32 s40, s29, s38
	s_cselect_b32 s39, s27, s60
	s_cselect_b32 s38, s58, s59
	s_add_i32 m0, s46, 0xc000
	s_nop 0
	global_load_lds_dwordx4 v134, s[36:37]
	s_add_i32 m0, s46, 0xe000
	s_nop 0
	global_load_lds_dwordx4 v132, s[36:37]
	ds_read_b128 v[140:143], v151
	ds_read_b128 v[144:147], v151 offset:1024
	ds_read_b128 v[156:159], v151 offset:2048
	ds_read_b128 v[160:163], v151 offset:3072
	ds_read_b128 v[164:167], v152
	ds_read_b128 v[168:171], v152 offset:1024
	ds_read_b128 v[172:175], v152 offset:2048
	ds_read_b128 v[176:179], v152 offset:3072
	ds_read_b128 v[180:183], v153
	ds_read_b128 v[184:187], v153 offset:1024
	ds_read_b128 v[188:191], v153 offset:2048
	ds_read_b128 v[192:195], v153 offset:3072
	ds_read_b128 v[196:199], v153 offset:4096
	ds_read_b128 v[200:203], v153 offset:5120
	ds_read_b128 v[208:211], v153 offset:6144
	ds_read_b128 v[212:215], v153 offset:7168
	s_waitcnt vmcnt(8)
	s_waitcnt lgkmcnt(0)
	s_barrier
	s_waitcnt lgkmcnt(0)
	v_mfma_f32_16x16x32_bf16 v[124:127], v[140:143], v[180:183], v[124:127]
	v_mfma_f32_16x16x32_bf16 v[120:123], v[156:159], v[180:183], v[120:123]
	v_mfma_f32_16x16x32_bf16 v[108:111], v[140:143], v[188:191], v[108:111]
	v_mfma_f32_16x16x32_bf16 v[104:107], v[156:159], v[188:191], v[104:107]
	v_mfma_f32_16x16x32_bf16 v[92:95], v[140:143], v[196:199], v[92:95]
	v_mfma_f32_16x16x32_bf16 v[88:91], v[156:159], v[196:199], v[88:91]
	v_mfma_f32_16x16x32_bf16 v[76:79], v[140:143], v[208:211], v[76:79]
	v_mfma_f32_16x16x32_bf16 v[72:75], v[156:159], v[208:211], v[72:75]
	v_mfma_f32_16x16x32_bf16 v[124:127], v[144:147], v[184:187], v[124:127]
	v_mfma_f32_16x16x32_bf16 v[120:123], v[160:163], v[184:187], v[120:123]
	v_mfma_f32_16x16x32_bf16 v[108:111], v[144:147], v[192:195], v[108:111]
	v_mfma_f32_16x16x32_bf16 v[104:107], v[160:163], v[192:195], v[104:107]
	v_mfma_f32_16x16x32_bf16 v[92:95], v[144:147], v[200:203], v[92:95]
	v_mfma_f32_16x16x32_bf16 v[88:91], v[160:163], v[200:203], v[88:91]
	v_mfma_f32_16x16x32_bf16 v[76:79], v[144:147], v[212:215], v[76:79]
	v_mfma_f32_16x16x32_bf16 v[72:75], v[160:163], v[212:215], v[72:75]
	v_mfma_f32_16x16x32_bf16 v[116:119], v[164:167], v[180:183], v[116:119]
	v_mfma_f32_16x16x32_bf16 v[112:115], v[172:175], v[180:183], v[112:115]
	v_mfma_f32_16x16x32_bf16 v[100:103], v[164:167], v[188:191], v[100:103]
	v_mfma_f32_16x16x32_bf16 v[96:99], v[172:175], v[188:191], v[96:99]
	v_mfma_f32_16x16x32_bf16 v[84:87], v[164:167], v[196:199], v[84:87]
	v_mfma_f32_16x16x32_bf16 v[80:83], v[172:175], v[196:199], v[80:83]
	v_mfma_f32_16x16x32_bf16 v[68:71], v[164:167], v[208:211], v[68:71]
	v_mfma_f32_16x16x32_bf16 v[64:67], v[172:175], v[208:211], v[64:67]
	v_mfma_f32_16x16x32_bf16 v[116:119], v[168:171], v[184:187], v[116:119]
	v_mfma_f32_16x16x32_bf16 v[112:115], v[176:179], v[184:187], v[112:115]
	v_mfma_f32_16x16x32_bf16 v[100:103], v[168:171], v[192:195], v[100:103]
	v_mfma_f32_16x16x32_bf16 v[96:99], v[176:179], v[192:195], v[96:99]
	v_mfma_f32_16x16x32_bf16 v[84:87], v[168:171], v[200:203], v[84:87]
	v_mfma_f32_16x16x32_bf16 v[80:83], v[176:179], v[200:203], v[80:83]
	v_mfma_f32_16x16x32_bf16 v[68:71], v[168:171], v[212:215], v[68:71]
	v_mfma_f32_16x16x32_bf16 v[64:67], v[176:179], v[212:215], v[64:67]
	s_barrier
	s_add_i32 s62, s54, s45
	s_mov_b32 m0, s62
	ds_read_b128 v[180:183], v153 offset:16384
	ds_read_b128 v[184:187], v153 offset:17408
	ds_read_b128 v[188:191], v153 offset:18432
	ds_read_b128 v[192:195], v153 offset:19456
	ds_read_b128 v[196:199], v153 offset:20480
	ds_read_b128 v[200:203], v153 offset:21504
	ds_read_b128 v[208:211], v153 offset:22528
	ds_read_b128 v[212:215], v153 offset:23552
	global_load_lds_dwordx4 v128, s[38:39]
	s_add_i32 m0, s62, 0x2000
	s_add_u32 s62, s38, 0x40000
	s_mov_b64 s[98:99], s[38:39]
	s_addc_u32 s63, s39, 0
	s_add_i32 s64, s55, s45
	global_load_lds_dwordx4 v130, s[38:39]
	s_mov_b32 m0, s64
	s_mov_b64 s[100:101], s[40:41]
	global_load_lds_dwordx4 v128, s[62:63]
	s_add_i32 m0, s64, 0x2000
	s_nop 0
	global_load_lds_dwordx4 v130, s[62:63]
	s_waitcnt vmcnt(6)
	s_waitcnt lgkmcnt(0)
	s_barrier
	s_waitcnt lgkmcnt(0)
	v_mfma_f32_16x16x32_bf16 v[60:63], v[140:143], v[180:183], v[60:63]
	v_mfma_f32_16x16x32_bf16 v[56:59], v[156:159], v[180:183], v[56:59]
	v_mfma_f32_16x16x32_bf16 v[44:47], v[140:143], v[188:191], v[44:47]
	v_mfma_f32_16x16x32_bf16 v[40:43], v[156:159], v[188:191], v[40:43]
	v_mfma_f32_16x16x32_bf16 v[28:31], v[140:143], v[196:199], v[28:31]
	v_mfma_f32_16x16x32_bf16 v[24:27], v[156:159], v[196:199], v[24:27]
	v_mfma_f32_16x16x32_bf16 v[12:15], v[140:143], v[208:211], v[12:15]
	v_mfma_f32_16x16x32_bf16 v[8:11], v[156:159], v[208:211], v[8:11]
	v_mfma_f32_16x16x32_bf16 v[60:63], v[144:147], v[184:187], v[60:63]
	v_mfma_f32_16x16x32_bf16 v[56:59], v[160:163], v[184:187], v[56:59]
	v_mfma_f32_16x16x32_bf16 v[44:47], v[144:147], v[192:195], v[44:47]
	v_mfma_f32_16x16x32_bf16 v[40:43], v[160:163], v[192:195], v[40:43]
	v_mfma_f32_16x16x32_bf16 v[28:31], v[144:147], v[200:203], v[28:31]
	v_mfma_f32_16x16x32_bf16 v[24:27], v[160:163], v[200:203], v[24:27]
	v_mfma_f32_16x16x32_bf16 v[12:15], v[144:147], v[212:215], v[12:15]
	v_mfma_f32_16x16x32_bf16 v[8:11], v[160:163], v[212:215], v[8:11]
	v_mfma_f32_16x16x32_bf16 v[52:55], v[164:167], v[180:183], v[52:55]
	v_mfma_f32_16x16x32_bf16 v[48:51], v[172:175], v[180:183], v[48:51]
	v_mfma_f32_16x16x32_bf16 v[36:39], v[164:167], v[188:191], v[36:39]
	v_mfma_f32_16x16x32_bf16 v[32:35], v[172:175], v[188:191], v[32:35]
	v_mfma_f32_16x16x32_bf16 v[20:23], v[164:167], v[196:199], v[20:23]
	v_mfma_f32_16x16x32_bf16 v[16:19], v[172:175], v[196:199], v[16:19]
	v_mfma_f32_16x16x32_bf16 v[4:7], v[164:167], v[208:211], v[4:7]
	v_mfma_f32_16x16x32_bf16 v[0:3], v[172:175], v[208:211], v[0:3]
	v_mfma_f32_16x16x32_bf16 v[52:55], v[168:171], v[184:187], v[52:55]
	v_mfma_f32_16x16x32_bf16 v[48:51], v[176:179], v[184:187], v[48:51]
	v_mfma_f32_16x16x32_bf16 v[36:39], v[168:171], v[192:195], v[36:39]
	v_mfma_f32_16x16x32_bf16 v[32:35], v[176:179], v[192:195], v[32:35]
	v_mfma_f32_16x16x32_bf16 v[20:23], v[168:171], v[200:203], v[20:23]
	v_mfma_f32_16x16x32_bf16 v[16:19], v[176:179], v[200:203], v[16:19]
	v_mfma_f32_16x16x32_bf16 v[4:7], v[168:171], v[212:215], v[4:7]
	v_mfma_f32_16x16x32_bf16 v[0:3], v[176:179], v[212:215], v[0:3]
	s_barrier
	s_mov_b32 m0, s46
	s_nop 0
	global_load_lds_dwordx4 v128, s[40:41]
	s_mov_b32 m0, s47
	s_nop 0
	global_load_lds_dwordx4 v130, s[40:41]
	s_add_i32 s62, 0, 0x18000
	s_add_i32 s63, 0, 0x1c000
	s_add_u32 s40, s40, 0x40000
	s_addc_u32 s41, s41, 0
	s_mov_b32 m0, s48
	s_nop 0
	global_load_lds_dwordx4 v128, s[40:41]
	s_mov_b32 m0, s49
	s_nop 0
	global_load_lds_dwordx4 v130, s[40:41]
	v_add_u32_e32 v155, s62, v149
	ds_read_b128 v[140:143], v155
	ds_read_b128 v[144:147], v155 offset:1024
	ds_read_b128 v[156:159], v155 offset:2048
	ds_read_b128 v[160:163], v155 offset:3072
	v_add_u32_e32 v155, s63, v149
	ds_read_b128 v[164:167], v155
	ds_read_b128 v[168:171], v155 offset:1024
	ds_read_b128 v[172:175], v155 offset:2048
	ds_read_b128 v[176:179], v155 offset:3072
	ds_read_b128 v[180:183], v153 offset:32768
	ds_read_b128 v[184:187], v153 offset:33792
	ds_read_b128 v[188:191], v153 offset:34816
	ds_read_b128 v[192:195], v153 offset:35840
	ds_read_b128 v[196:199], v153 offset:36864
	ds_read_b128 v[200:203], v153 offset:37888
	ds_read_b128 v[208:211], v153 offset:38912
	ds_read_b128 v[212:215], v153 offset:39936
	s_waitcnt vmcnt(8)
	s_waitcnt lgkmcnt(0)
	s_barrier
	s_waitcnt lgkmcnt(0)
	v_mfma_f32_16x16x32_bf16 v[124:127], v[140:143], v[180:183], v[124:127]
	v_mfma_f32_16x16x32_bf16 v[120:123], v[156:159], v[180:183], v[120:123]
	v_mfma_f32_16x16x32_bf16 v[108:111], v[140:143], v[188:191], v[108:111]
	v_mfma_f32_16x16x32_bf16 v[104:107], v[156:159], v[188:191], v[104:107]
	v_mfma_f32_16x16x32_bf16 v[92:95], v[140:143], v[196:199], v[92:95]
	v_mfma_f32_16x16x32_bf16 v[88:91], v[156:159], v[196:199], v[88:91]
	v_mfma_f32_16x16x32_bf16 v[76:79], v[140:143], v[208:211], v[76:79]
	v_mfma_f32_16x16x32_bf16 v[72:75], v[156:159], v[208:211], v[72:75]
	v_mfma_f32_16x16x32_bf16 v[124:127], v[144:147], v[184:187], v[124:127]
	v_mfma_f32_16x16x32_bf16 v[120:123], v[160:163], v[184:187], v[120:123]
	v_mfma_f32_16x16x32_bf16 v[108:111], v[144:147], v[192:195], v[108:111]
	v_mfma_f32_16x16x32_bf16 v[104:107], v[160:163], v[192:195], v[104:107]
	v_mfma_f32_16x16x32_bf16 v[92:95], v[144:147], v[200:203], v[92:95]
	v_mfma_f32_16x16x32_bf16 v[88:91], v[160:163], v[200:203], v[88:91]
	v_mfma_f32_16x16x32_bf16 v[76:79], v[144:147], v[212:215], v[76:79]
	v_mfma_f32_16x16x32_bf16 v[72:75], v[160:163], v[212:215], v[72:75]
	v_mfma_f32_16x16x32_bf16 v[116:119], v[164:167], v[180:183], v[116:119]
	v_mfma_f32_16x16x32_bf16 v[112:115], v[172:175], v[180:183], v[112:115]
	v_mfma_f32_16x16x32_bf16 v[100:103], v[164:167], v[188:191], v[100:103]
	v_mfma_f32_16x16x32_bf16 v[96:99], v[172:175], v[188:191], v[96:99]
	v_mfma_f32_16x16x32_bf16 v[84:87], v[164:167], v[196:199], v[84:87]
	v_mfma_f32_16x16x32_bf16 v[80:83], v[172:175], v[196:199], v[80:83]
	v_mfma_f32_16x16x32_bf16 v[68:71], v[164:167], v[208:211], v[68:71]
	v_mfma_f32_16x16x32_bf16 v[64:67], v[172:175], v[208:211], v[64:67]
	v_mfma_f32_16x16x32_bf16 v[116:119], v[168:171], v[184:187], v[116:119]
	v_mfma_f32_16x16x32_bf16 v[112:115], v[176:179], v[184:187], v[112:115]
	v_mfma_f32_16x16x32_bf16 v[100:103], v[168:171], v[192:195], v[100:103]
	v_mfma_f32_16x16x32_bf16 v[96:99], v[176:179], v[192:195], v[96:99]
	v_mfma_f32_16x16x32_bf16 v[84:87], v[168:171], v[200:203], v[84:87]
	v_mfma_f32_16x16x32_bf16 v[80:83], v[176:179], v[200:203], v[80:83]
	v_mfma_f32_16x16x32_bf16 v[68:71], v[168:171], v[212:215], v[68:71]
	v_mfma_f32_16x16x32_bf16 v[64:67], v[176:179], v[212:215], v[64:67]
	s_barrier
	s_add_i32 s40, s62, s45
	s_mov_b32 m0, s40
	ds_read_b128 v[180:183], v153 offset:49152
	ds_read_b128 v[184:187], v153 offset:50176
	ds_read_b128 v[188:191], v153 offset:51200
	ds_read_b128 v[192:195], v153 offset:52224
	ds_read_b128 v[196:199], v153 offset:53248
	ds_read_b128 v[200:203], v153 offset:54272
	ds_read_b128 v[208:211], v153 offset:55296
	ds_read_b128 v[212:215], v153 offset:56320
	global_load_lds_dwordx4 v204, s[38:39]
	s_add_i32 m0, s40, 0x2000
	s_add_u32 s38, s38, 0x40080
	s_addc_u32 s39, s39, 0
	s_add_i32 s40, s63, s45
	global_load_lds_dwordx4 v205, s[98:99]
	s_mov_b32 m0, s40
	s_nop 0
	global_load_lds_dwordx4 v128, s[38:39]
	s_add_i32 m0, s40, 0x2000
	s_nop 0
	global_load_lds_dwordx4 v130, s[38:39]
	s_cmp_lg_u32 s61, 12
	s_cbranch_scc1 .Lbal_last_11
	s_mov_b32 m0, s51
	s_nop 0
	global_load_lds_dwordx4 v204, s[100:101]
	s_mov_b32 m0, s52
	s_nop 0
	global_load_lds_dwordx4 v205, s[100:101]

.Lbal_first_10:
	s_add_u32 s26, s24, 0xfffc0080
	s_addc_u32 s27, s25, -1
	s_cmp_eq_u32 s54, 12
	s_cselect_b32 s29, s19, s27
	s_cselect_b32 s28, s50, s26
	s_cselect_b32 s27, s17, s53
	s_cselect_b32 s26, s51, s52
	s_add_i32 m0, s38, 0xc000
	s_nop 0
	global_load_lds_dwordx4 v138, s[24:25]
	s_add_i32 m0, s38, 0xe000
	s_nop 0
	global_load_lds_dwordx4 v136, s[24:25]
	ds_read_b128 v[144:147], v151
	ds_read_b128 v[156:159], v151 offset:1024
	ds_read_b128 v[160:163], v151 offset:2048
	ds_read_b128 v[164:167], v151 offset:3072
	ds_read_b128 v[168:171], v152
	ds_read_b128 v[172:175], v152 offset:1024
	ds_read_b128 v[176:179], v152 offset:2048
	ds_read_b128 v[180:183], v152 offset:3072
	ds_read_b128 v[184:187], v153
	ds_read_b128 v[188:191], v153 offset:1024
	ds_read_b128 v[192:195], v153 offset:2048
	ds_read_b128 v[196:199], v153 offset:3072
	ds_read_b128 v[200:203], v153 offset:4096
	ds_read_b128 v[208:211], v153 offset:5120
	ds_read_b128 v[212:215], v153 offset:6144
	ds_read_b128 v[216:219], v153 offset:7168
	s_waitcnt vmcnt(8)
	s_waitcnt lgkmcnt(0)
	s_barrier
	s_waitcnt lgkmcnt(0)
	v_mfma_f32_16x16x32_bf16 v[124:127], v[144:147], v[184:187], v[124:127]
	v_mfma_f32_16x16x32_bf16 v[120:123], v[160:163], v[184:187], v[120:123]
	v_mfma_f32_16x16x32_bf16 v[108:111], v[144:147], v[192:195], v[108:111]
	v_mfma_f32_16x16x32_bf16 v[104:107], v[160:163], v[192:195], v[104:107]
	v_mfma_f32_16x16x32_bf16 v[92:95], v[144:147], v[200:203], v[92:95]
	v_mfma_f32_16x16x32_bf16 v[88:91], v[160:163], v[200:203], v[88:91]
	v_mfma_f32_16x16x32_bf16 v[76:79], v[144:147], v[212:215], v[76:79]
	v_mfma_f32_16x16x32_bf16 v[72:75], v[160:163], v[212:215], v[72:75]
	v_mfma_f32_16x16x32_bf16 v[124:127], v[156:159], v[188:191], v[124:127]
	v_mfma_f32_16x16x32_bf16 v[120:123], v[164:167], v[188:191], v[120:123]
	v_mfma_f32_16x16x32_bf16 v[108:111], v[156:159], v[196:199], v[108:111]
	v_mfma_f32_16x16x32_bf16 v[104:107], v[164:167], v[196:199], v[104:107]
	v_mfma_f32_16x16x32_bf16 v[92:95], v[156:159], v[208:211], v[92:95]
	v_mfma_f32_16x16x32_bf16 v[88:91], v[164:167], v[208:211], v[88:91]
	v_mfma_f32_16x16x32_bf16 v[76:79], v[156:159], v[216:219], v[76:79]
	v_mfma_f32_16x16x32_bf16 v[72:75], v[164:167], v[216:219], v[72:75]
	v_mfma_f32_16x16x32_bf16 v[116:119], v[168:171], v[184:187], v[116:119]
	v_mfma_f32_16x16x32_bf16 v[112:115], v[176:179], v[184:187], v[112:115]
	v_mfma_f32_16x16x32_bf16 v[100:103], v[168:171], v[192:195], v[100:103]
	v_mfma_f32_16x16x32_bf16 v[96:99], v[176:179], v[192:195], v[96:99]
	v_mfma_f32_16x16x32_bf16 v[84:87], v[168:171], v[200:203], v[84:87]
	v_mfma_f32_16x16x32_bf16 v[80:83], v[176:179], v[200:203], v[80:83]
	v_mfma_f32_16x16x32_bf16 v[68:71], v[168:171], v[212:215], v[68:71]
	v_mfma_f32_16x16x32_bf16 v[64:67], v[176:179], v[212:215], v[64:67]
	v_mfma_f32_16x16x32_bf16 v[116:119], v[172:175], v[188:191], v[116:119]
	v_mfma_f32_16x16x32_bf16 v[112:115], v[180:183], v[188:191], v[112:115]
	v_mfma_f32_16x16x32_bf16 v[100:103], v[172:175], v[196:199], v[100:103]
	v_mfma_f32_16x16x32_bf16 v[96:99], v[180:183], v[196:199], v[96:99]
	v_mfma_f32_16x16x32_bf16 v[84:87], v[172:175], v[208:211], v[84:87]
	v_mfma_f32_16x16x32_bf16 v[80:83], v[180:183], v[208:211], v[80:83]
	v_mfma_f32_16x16x32_bf16 v[68:71], v[172:175], v[216:219], v[68:71]
	v_mfma_f32_16x16x32_bf16 v[64:67], v[180:183], v[216:219], v[64:67]
	s_barrier
	s_add_i32 s55, s47, s35
	s_mov_b32 m0, s55
	ds_read_b128 v[184:187], v153 offset:16384
	ds_read_b128 v[188:191], v153 offset:17408
	ds_read_b128 v[192:195], v153 offset:18432
	ds_read_b128 v[196:199], v153 offset:19456
	ds_read_b128 v[200:203], v153 offset:20480
	ds_read_b128 v[208:211], v153 offset:21504
	ds_read_b128 v[212:215], v153 offset:22528
	ds_read_b128 v[216:219], v153 offset:23552
	global_load_lds_dwordx4 v132, s[26:27]
	s_add_i32 m0, s55, 0x2000
	s_add_u32 s56, s26, 0x40000
	s_mov_b64 s[98:99], s[26:27]
	s_addc_u32 s57, s27, 0
	s_add_i32 s55, s48, s35
	global_load_lds_dwordx4 v128, s[26:27]
	s_mov_b32 m0, s55
	s_mov_b64 s[100:101], s[28:29]
	global_load_lds_dwordx4 v132, s[56:57]
	s_add_i32 m0, s55, 0x2000
	s_nop 0
	global_load_lds_dwordx4 v128, s[56:57]
	s_waitcnt vmcnt(6)
	s_waitcnt lgkmcnt(0)
	s_barrier
	s_waitcnt lgkmcnt(0)
	v_mfma_f32_16x16x32_bf16 v[60:63], v[144:147], v[184:187], v[60:63]
	v_mfma_f32_16x16x32_bf16 v[56:59], v[160:163], v[184:187], v[56:59]
	v_mfma_f32_16x16x32_bf16 v[44:47], v[144:147], v[192:195], v[44:47]
	v_mfma_f32_16x16x32_bf16 v[40:43], v[160:163], v[192:195], v[40:43]
	v_mfma_f32_16x16x32_bf16 v[28:31], v[144:147], v[200:203], v[28:31]
	v_mfma_f32_16x16x32_bf16 v[24:27], v[160:163], v[200:203], v[24:27]
	v_mfma_f32_16x16x32_bf16 v[12:15], v[144:147], v[212:215], v[12:15]
	v_mfma_f32_16x16x32_bf16 v[8:11], v[160:163], v[212:215], v[8:11]
	v_mfma_f32_16x16x32_bf16 v[60:63], v[156:159], v[188:191], v[60:63]
	v_mfma_f32_16x16x32_bf16 v[56:59], v[164:167], v[188:191], v[56:59]
	v_mfma_f32_16x16x32_bf16 v[44:47], v[156:159], v[196:199], v[44:47]
	v_mfma_f32_16x16x32_bf16 v[40:43], v[164:167], v[196:199], v[40:43]
	v_mfma_f32_16x16x32_bf16 v[28:31], v[156:159], v[208:211], v[28:31]
	v_mfma_f32_16x16x32_bf16 v[24:27], v[164:167], v[208:211], v[24:27]
	v_mfma_f32_16x16x32_bf16 v[12:15], v[156:159], v[216:219], v[12:15]
	v_mfma_f32_16x16x32_bf16 v[8:11], v[164:167], v[216:219], v[8:11]
	v_mfma_f32_16x16x32_bf16 v[52:55], v[168:171], v[184:187], v[52:55]
	v_mfma_f32_16x16x32_bf16 v[48:51], v[176:179], v[184:187], v[48:51]
	v_mfma_f32_16x16x32_bf16 v[36:39], v[168:171], v[192:195], v[36:39]
	v_mfma_f32_16x16x32_bf16 v[32:35], v[176:179], v[192:195], v[32:35]
	v_mfma_f32_16x16x32_bf16 v[20:23], v[168:171], v[200:203], v[20:23]
	v_mfma_f32_16x16x32_bf16 v[16:19], v[176:179], v[200:203], v[16:19]
	v_mfma_f32_16x16x32_bf16 v[4:7], v[168:171], v[212:215], v[4:7]
	v_mfma_f32_16x16x32_bf16 v[0:3], v[176:179], v[212:215], v[0:3]
	v_mfma_f32_16x16x32_bf16 v[52:55], v[172:175], v[188:191], v[52:55]
	v_mfma_f32_16x16x32_bf16 v[48:51], v[180:183], v[188:191], v[48:51]
	v_mfma_f32_16x16x32_bf16 v[36:39], v[172:175], v[196:199], v[36:39]
	v_mfma_f32_16x16x32_bf16 v[32:35], v[180:183], v[196:199], v[32:35]
	v_mfma_f32_16x16x32_bf16 v[20:23], v[172:175], v[208:211], v[20:23]
	v_mfma_f32_16x16x32_bf16 v[16:19], v[180:183], v[208:211], v[16:19]
	v_mfma_f32_16x16x32_bf16 v[4:7], v[172:175], v[216:219], v[4:7]
	v_mfma_f32_16x16x32_bf16 v[0:3], v[180:183], v[216:219], v[0:3]
	s_barrier
	s_mov_b32 m0, s38
	s_nop 0
	global_load_lds_dwordx4 v134, s[28:29]
	s_mov_b32 m0, s39
	s_nop 0
	global_load_lds_dwordx4 v130, s[28:29]
	s_add_i32 s55, 0, 0x18000
	s_add_i32 s56, 0, 0x1c000
	s_add_u32 s28, s28, 0x40000
	s_addc_u32 s29, s29, 0
	s_mov_b32 m0, s40
	s_nop 0
	global_load_lds_dwordx4 v134, s[28:29]
	s_mov_b32 m0, s41
	s_nop 0
	global_load_lds_dwordx4 v130, s[28:29]
	v_add_u32_e32 v164, s55, v149
	v_add_u32_e32 v180, s56, v149
	ds_read_b128 v[144:147], v164
	ds_read_b128 v[156:159], v164 offset:1024
	ds_read_b128 v[160:163], v164 offset:2048
	ds_read_b128 v[164:167], v164 offset:3072
	ds_read_b128 v[168:171], v180
	ds_read_b128 v[172:175], v180 offset:1024
	ds_read_b128 v[176:179], v180 offset:2048
	ds_read_b128 v[180:183], v180 offset:3072
	ds_read_b128 v[184:187], v153 offset:32768
	ds_read_b128 v[188:191], v153 offset:33792
	ds_read_b128 v[192:195], v153 offset:34816
	ds_read_b128 v[196:199], v153 offset:35840
	ds_read_b128 v[200:203], v153 offset:36864
	ds_read_b128 v[208:211], v153 offset:37888
	ds_read_b128 v[212:215], v153 offset:38912
	ds_read_b128 v[216:219], v153 offset:39936
	s_waitcnt vmcnt(8)
	s_waitcnt lgkmcnt(0)
	s_barrier
	s_waitcnt lgkmcnt(0)
	v_mfma_f32_16x16x32_bf16 v[124:127], v[144:147], v[184:187], v[124:127]
	v_mfma_f32_16x16x32_bf16 v[120:123], v[160:163], v[184:187], v[120:123]
	v_mfma_f32_16x16x32_bf16 v[108:111], v[144:147], v[192:195], v[108:111]
	v_mfma_f32_16x16x32_bf16 v[104:107], v[160:163], v[192:195], v[104:107]
	v_mfma_f32_16x16x32_bf16 v[92:95], v[144:147], v[200:203], v[92:95]
	v_mfma_f32_16x16x32_bf16 v[88:91], v[160:163], v[200:203], v[88:91]
	v_mfma_f32_16x16x32_bf16 v[76:79], v[144:147], v[212:215], v[76:79]
	v_mfma_f32_16x16x32_bf16 v[72:75], v[160:163], v[212:215], v[72:75]
	v_mfma_f32_16x16x32_bf16 v[124:127], v[156:159], v[188:191], v[124:127]
	v_mfma_f32_16x16x32_bf16 v[120:123], v[164:167], v[188:191], v[120:123]
	v_mfma_f32_16x16x32_bf16 v[108:111], v[156:159], v[196:199], v[108:111]
	v_mfma_f32_16x16x32_bf16 v[104:107], v[164:167], v[196:199], v[104:107]
	v_mfma_f32_16x16x32_bf16 v[92:95], v[156:159], v[208:211], v[92:95]
	v_mfma_f32_16x16x32_bf16 v[88:91], v[164:167], v[208:211], v[88:91]
	v_mfma_f32_16x16x32_bf16 v[76:79], v[156:159], v[216:219], v[76:79]
	v_mfma_f32_16x16x32_bf16 v[72:75], v[164:167], v[216:219], v[72:75]
	v_mfma_f32_16x16x32_bf16 v[116:119], v[168:171], v[184:187], v[116:119]
	v_mfma_f32_16x16x32_bf16 v[112:115], v[176:179], v[184:187], v[112:115]
	v_mfma_f32_16x16x32_bf16 v[100:103], v[168:171], v[192:195], v[100:103]
	v_mfma_f32_16x16x32_bf16 v[96:99], v[176:179], v[192:195], v[96:99]
	v_mfma_f32_16x16x32_bf16 v[84:87], v[168:171], v[200:203], v[84:87]
	v_mfma_f32_16x16x32_bf16 v[80:83], v[176:179], v[200:203], v[80:83]
	v_mfma_f32_16x16x32_bf16 v[68:71], v[168:171], v[212:215], v[68:71]
	v_mfma_f32_16x16x32_bf16 v[64:67], v[176:179], v[212:215], v[64:67]
	v_mfma_f32_16x16x32_bf16 v[116:119], v[172:175], v[188:191], v[116:119]
	v_mfma_f32_16x16x32_bf16 v[112:115], v[180:183], v[188:191], v[112:115]
	v_mfma_f32_16x16x32_bf16 v[100:103], v[172:175], v[196:199], v[100:103]
	v_mfma_f32_16x16x32_bf16 v[96:99], v[180:183], v[196:199], v[96:99]
	v_mfma_f32_16x16x32_bf16 v[84:87], v[172:175], v[208:211], v[84:87]
	v_mfma_f32_16x16x32_bf16 v[80:83], v[180:183], v[208:211], v[80:83]
	v_mfma_f32_16x16x32_bf16 v[68:71], v[172:175], v[216:219], v[68:71]
	v_mfma_f32_16x16x32_bf16 v[64:67], v[180:183], v[216:219], v[64:67]
	s_barrier
	s_add_i32 s28, s55, s35
	s_mov_b32 m0, s28
	ds_read_b128 v[184:187], v153 offset:49152
	ds_read_b128 v[188:191], v153 offset:50176
	ds_read_b128 v[192:195], v153 offset:51200
	ds_read_b128 v[196:199], v153 offset:52224
	ds_read_b128 v[200:203], v153 offset:53248
	ds_read_b128 v[208:211], v153 offset:54272
	ds_read_b128 v[212:215], v153 offset:55296
	ds_read_b128 v[216:219], v153 offset:56320
	global_load_lds_dwordx4 v220, s[26:27]
	s_add_i32 m0, s28, 0x2000
	s_add_u32 s26, s26, 0x40080
	s_addc_u32 s27, s27, 0
	s_add_i32 s28, s56, s35
	global_load_lds_dwordx4 v204, s[98:99]
	s_mov_b32 m0, s28
	s_nop 0
	global_load_lds_dwordx4 v132, s[26:27]
	s_add_i32 m0, s28, 0x2000
	s_nop 0
	global_load_lds_dwordx4 v128, s[26:27]
	s_cmp_lg_u32 s54, 12
	s_cbranch_scc1 .Lbal_last_10
	s_mov_b32 m0, s45
	s_nop 0
	global_load_lds_dwordx4 v221, s[100:101]
	s_mov_b32 m0, s46
	s_nop 0
	global_load_lds_dwordx4 v205, s[100:101]
